# nt hint on streaming residual loads and f32 result stores in FFN1-down, w_o and FFN2-down epilogues
# speedup vs baseline: 1.0044x; 1.0031x over previous
; __device__ __forceinline__ unsigned cvt_pk_bf16(float lo, float hi) { f32x2 v = {lo, hi}; bf16x2_t b = __builtin_convertvector(v, bf16x2_t); return __builtin_bit_cast(unsigned, b); }
;     __device__ __forceinline__ void operator()(const f32x4 (&acc)[2][2][4][2], const Unit& u, int wr, int wc, int fr, int fq) const {
;         const int row0 = u.pm * BM + wr * 64 + fr, col0 = u.pn * BM + wc * 32 + 4 * fq;
; #pragma unroll
;         for (int ai = 0; ai < 2; ++ai) {
;             f32x4 bs[4][2][2];
; #pragma unroll
;             for (int m = 0; m < 4; ++m)
; #pragma unroll
;                 for (int bj = 0; bj < 2; ++bj)
; #pragma unroll
;                     for (int n = 0; n < 2; ++n) bs[m][bj][n] = *(const f32x4*)(base + (size_t)(row0 + ai * HALF + m * 16) * DMODEL + col0 + bj * HALF + n * 16);
; #pragma unroll
;             for (int m = 0; m < 4; ++m) { const int row = row0 + ai * HALF + m * 16; const size_t off = (size_t)row * DMODEL + col0; float sq = 0.f;
; #pragma unroll
;                 for (int bj = 0; bj < 2; ++bj)
; #pragma unroll
;                     for (int n = 0; n < 2; ++n) { const size_t o2 = off + bj * HALF + n * 16; const f32x4 o = bs[m][bj][n] + acc[ai][bj][m][n] * alpha;
;                         *(f32x4*)(out + o2) = o; sq += (o[0] * o[0] + o[1] * o[1]) + (o[2] * o[2] + o[3] * o[3]);
;                         if (outb) { u32x2 w; w.x = cvt_pk_bf16(o[0], o[1]); w.y = cvt_pk_bf16(o[2], o[3]); *(u32x2*)(outb + o2) = w; } }
.LBB0_251:
	v_lshl_add_u32 v204, s13, 8, v217
	v_lshl_or_b32 v200, s12, 8, v219
	v_ashrrev_i32_e32 v201, 31, v200
	v_ashrrev_i32_e32 v205, 31, v204
	v_lshl_add_u64 v[202:203], v[200:201], 2, s[36:37]
	v_lshlrev_b64 v[128:129], 13, v[204:205]
	v_or_b32_e32 v210, 16, v204
	v_lshl_add_u64 v[128:129], v[202:203], 0, v[128:129]
	v_ashrrev_i32_e32 v211, 31, v210
	global_load_dwordx4 v[226:229], v[128:129], off nt
	global_load_dwordx4 v[184:187], v[128:129], off offset:64 nt
	global_load_dwordx4 v[180:183], v[128:129], off offset:512 nt
	global_load_dwordx4 v[176:179], v[128:129], off offset:576 nt
	v_lshlrev_b64 v[128:129], 13, v[210:211]
	v_or_b32_e32 v208, 32, v204
	v_lshl_add_u64 v[128:129], v[202:203], 0, v[128:129]
	v_ashrrev_i32_e32 v209, 31, v208
	global_load_dwordx4 v[172:175], v[128:129], off nt
	global_load_dwordx4 v[168:171], v[128:129], off offset:64 nt
	global_load_dwordx4 v[164:167], v[128:129], off offset:512 nt
	global_load_dwordx4 v[160:163], v[128:129], off offset:576 nt
	v_lshlrev_b64 v[128:129], 13, v[208:209]
	v_or_b32_e32 v206, 48, v204
	v_lshl_add_u64 v[128:129], v[202:203], 0, v[128:129]
	v_ashrrev_i32_e32 v207, 31, v206
	global_load_dwordx4 v[156:159], v[128:129], off nt
	global_load_dwordx4 v[152:155], v[128:129], off offset:64 nt
	global_load_dwordx4 v[148:151], v[128:129], off offset:512 nt
	global_load_dwordx4 v[144:147], v[128:129], off offset:576 nt
	v_lshlrev_b64 v[128:129], 13, v[206:207]
	v_lshl_add_u64 v[128:129], v[202:203], 0, v[128:129]
	global_load_dwordx4 v[140:143], v[128:129], off nt
	global_load_dwordx4 v[136:139], v[128:129], off offset:64 nt
	global_load_dwordx4 v[132:135], v[128:129], off offset:512 nt
	s_nop 0
	global_load_dwordx4 v[128:131], v[128:129], off offset:576 nt
	v_lshlrev_b64 v[212:213], 11, v[204:205]
	v_lshl_add_u64 v[214:215], v[212:213], 0, v[200:201]
	v_cndmask_b32_e64 v225, 0, 1, s[24:25]
	v_lshl_add_u64 v[212:213], v[214:215], 2, s[56:57]
	v_cmp_ne_u32_e64 s[10:11], 1, v225
	s_andn2_b64 vcc, exec, s[24:25]
	s_waitcnt vmcnt(0)
	v_pk_fma_f32 v[126:127], v[126:127], 0.5, v[228:229] op_sel_hi:[1,0,1]
	v_pk_fma_f32 v[124:125], v[124:125], 0.5, v[226:227] op_sel_hi:[1,0,1]
	global_store_dwordx4 v[212:213], v[124:127], off nt
	s_cbranch_vccnz .LBB0_253
	v_cvt_pk_bf16_f32 v226, v124, v125
	v_cvt_pk_bf16_f32 v227, v126, v127
	v_lshl_add_u64 v[228:229], v[214:215], 1, s[40:41]
	global_store_dwordx2 v[228:229], v[226:227], off
.LBB0_253:
	v_pk_fma_f32 v[122:123], v[122:123], 0.5, v[186:187] op_sel_hi:[1,0,1]
	v_pk_fma_f32 v[120:121], v[120:121], 0.5, v[184:185] op_sel_hi:[1,0,1]
	s_and_b64 vcc, exec, s[10:11]
	v_lshlrev_b64 v[184:185], 1, v[214:215]
	global_store_dwordx4 v[212:213], v[120:123], off offset:64 nt
	s_cbranch_vccnz .LBB0_255
	v_or_b32_e32 v214, 32, v184
	v_mov_b32_e32 v215, v185
	v_cvt_pk_bf16_f32 v186, v120, v121
	v_cvt_pk_bf16_f32 v187, v122, v123
	v_lshl_add_u64 v[214:215], s[40:41], 0, v[214:215]
	global_store_dwordx2 v[214:215], v[186:187], off
.LBB0_255:
	v_pk_fma_f32 v[118:119], v[118:119], 0.5, v[182:183] op_sel_hi:[1,0,1]
	v_pk_fma_f32 v[116:117], v[116:117], 0.5, v[180:181] op_sel_hi:[1,0,1]
	s_and_b64 vcc, exec, s[10:11]
	global_store_dwordx4 v[212:213], v[116:119], off offset:512 nt
	s_cbranch_vccnz .LBB0_257
	v_or_b32_e32 v182, 0x100, v184
	v_mov_b32_e32 v183, v185
	v_cvt_pk_bf16_f32 v180, v116, v117
	v_cvt_pk_bf16_f32 v181, v118, v119
	v_lshl_add_u64 v[182:183], s[40:41], 0, v[182:183]
	global_store_dwordx2 v[182:183], v[180:181], off
.LBB0_257:
	v_pk_fma_f32 v[114:115], v[114:115], 0.5, v[178:179] op_sel_hi:[1,0,1]
	v_pk_fma_f32 v[112:113], v[112:113], 0.5, v[176:177] op_sel_hi:[1,0,1]
	s_and_b64 vcc, exec, s[10:11]
	global_store_dwordx4 v[212:213], v[112:115], off offset:576 nt
	s_cbranch_vccnz .LBB0_259
	v_or_b32_e32 v184, 0x120, v184
	v_cvt_pk_bf16_f32 v176, v112, v113
	v_cvt_pk_bf16_f32 v177, v114, v115
	v_lshl_add_u64 v[178:179], s[40:41], 0, v[184:185]
	global_store_dwordx2 v[178:179], v[176:177], off

; __device__ __forceinline__ unsigned cvt_pk_bf16(float lo, float hi) { f32x2 v = {lo, hi}; bf16x2_t b = __builtin_convertvector(v, bf16x2_t); return __builtin_bit_cast(unsigned, b); }
;     __device__ __forceinline__ void operator()(const f32x4 (&acc)[2][2][4][2], const Unit& u, int wr, int wc, int fr, int fq) const {
;     ...
;             for (int m = 0; m < 4; ++m) { const int row = row0 + ai * HALF + m * 16; const size_t off = (size_t)row * DMODEL + col0; float sq = 0.f;
; #pragma unroll
;                 for (int bj = 0; bj < 2; ++bj)
; #pragma unroll
;                     for (int n = 0; n < 2; ++n) { const size_t o2 = off + bj * HALF + n * 16; const f32x4 o = bs[m][bj][n] + acc[ai][bj][m][n] * alpha;
;                         *(f32x4*)(out + o2) = o; sq += (o[0] * o[0] + o[1] * o[1]) + (o[2] * o[2] + o[3] * o[3]);
;                         if (outb) { u32x2 w; w.x = cvt_pk_bf16(o[0], o[1]); w.y = cvt_pk_bf16(o[2], o[3]); *(u32x2*)(outb + o2) = w; } }
.LBB0_261:
	s_or_b64 exec, exec, s[12:13]
	s_waitcnt lgkmcnt(0)
	v_lshlrev_b64 v[112:113], 11, v[210:211]
	v_lshl_add_u64 v[114:115], v[112:113], 0, v[200:201]
	v_pk_fma_f32 v[110:111], v[110:111], 0.5, v[174:175] op_sel_hi:[1,0,1]
	v_pk_fma_f32 v[108:109], v[108:109], 0.5, v[172:173] op_sel_hi:[1,0,1]
	v_lshl_add_u64 v[112:113], v[114:115], 2, s[56:57]
	s_and_b64 vcc, exec, s[10:11]
	global_store_dwordx4 v[112:113], v[108:111], off nt
	s_cbranch_vccnz .LBB0_263
	v_cvt_pk_bf16_f32 v116, v108, v109
	v_cvt_pk_bf16_f32 v117, v110, v111
	v_lshl_add_u64 v[118:119], v[114:115], 1, s[40:41]
	global_store_dwordx2 v[118:119], v[116:117], off
.LBB0_263:
	v_pk_fma_f32 v[106:107], v[106:107], 0.5, v[170:171] op_sel_hi:[1,0,1]
	v_pk_fma_f32 v[104:105], v[104:105], 0.5, v[168:169] op_sel_hi:[1,0,1]
	s_and_b64 vcc, exec, s[10:11]
	v_lshlrev_b64 v[114:115], 1, v[114:115]
	global_store_dwordx4 v[112:113], v[104:107], off offset:64 nt
	s_cbranch_vccnz .LBB0_265
	v_or_b32_e32 v118, 32, v114
	v_mov_b32_e32 v119, v115
	v_cvt_pk_bf16_f32 v116, v104, v105
	v_cvt_pk_bf16_f32 v117, v106, v107
	v_lshl_add_u64 v[118:119], s[40:41], 0, v[118:119]
	global_store_dwordx2 v[118:119], v[116:117], off
.LBB0_265:
	v_pk_fma_f32 v[102:103], v[102:103], 0.5, v[166:167] op_sel_hi:[1,0,1]
	v_pk_fma_f32 v[100:101], v[100:101], 0.5, v[164:165] op_sel_hi:[1,0,1]
	s_and_b64 vcc, exec, s[10:11]
	global_store_dwordx4 v[112:113], v[100:103], off offset:512 nt
	s_cbranch_vccnz .LBB0_267
	v_or_b32_e32 v118, 0x100, v114
	v_mov_b32_e32 v119, v115
	v_cvt_pk_bf16_f32 v116, v100, v101
	v_cvt_pk_bf16_f32 v117, v102, v103
	v_lshl_add_u64 v[118:119], s[40:41], 0, v[118:119]
	global_store_dwordx2 v[118:119], v[116:117], off
.LBB0_267:
	v_pk_fma_f32 v[98:99], v[98:99], 0.5, v[162:163] op_sel_hi:[1,0,1]
	v_pk_fma_f32 v[96:97], v[96:97], 0.5, v[160:161] op_sel_hi:[1,0,1]
	s_and_b64 vcc, exec, s[10:11]
	global_store_dwordx4 v[112:113], v[96:99], off offset:576 nt
	s_cbranch_vccnz .LBB0_269
	v_or_b32_e32 v114, 0x120, v114
	v_cvt_pk_bf16_f32 v112, v96, v97
	v_cvt_pk_bf16_f32 v113, v98, v99
	v_lshl_add_u64 v[114:115], s[40:41], 0, v[114:115]
	global_store_dwordx2 v[114:115], v[112:113], off

; __device__ __forceinline__ unsigned cvt_pk_bf16(float lo, float hi) { f32x2 v = {lo, hi}; bf16x2_t b = __builtin_convertvector(v, bf16x2_t); return __builtin_bit_cast(unsigned, b); }
;     __device__ __forceinline__ void operator()(const f32x4 (&acc)[2][2][4][2], const Unit& u, int wr, int wc, int fr, int fq) const {
;     ...
;             for (int m = 0; m < 4; ++m) { const int row = row0 + ai * HALF + m * 16; const size_t off = (size_t)row * DMODEL + col0; float sq = 0.f;
; #pragma unroll
;                 for (int bj = 0; bj < 2; ++bj)
; #pragma unroll
;                     for (int n = 0; n < 2; ++n) { const size_t o2 = off + bj * HALF + n * 16; const f32x4 o = bs[m][bj][n] + acc[ai][bj][m][n] * alpha;
;                         *(f32x4*)(out + o2) = o; sq += (o[0] * o[0] + o[1] * o[1]) + (o[2] * o[2] + o[3] * o[3]);
;                         if (outb) { u32x2 w; w.x = cvt_pk_bf16(o[0], o[1]); w.y = cvt_pk_bf16(o[2], o[3]); *(u32x2*)(outb + o2) = w; } }
.LBB0_271:
	s_or_b64 exec, exec, s[12:13]
	s_waitcnt lgkmcnt(0)
	v_lshlrev_b64 v[96:97], 11, v[208:209]
	v_lshl_add_u64 v[98:99], v[96:97], 0, v[200:201]
	v_pk_fma_f32 v[94:95], v[94:95], 0.5, v[158:159] op_sel_hi:[1,0,1]
	v_pk_fma_f32 v[92:93], v[92:93], 0.5, v[156:157] op_sel_hi:[1,0,1]
	v_lshl_add_u64 v[96:97], v[98:99], 2, s[56:57]
	s_and_b64 vcc, exec, s[10:11]
	global_store_dwordx4 v[96:97], v[92:95], off nt
	s_cbranch_vccnz .LBB0_273
	v_cvt_pk_bf16_f32 v100, v92, v93
	v_cvt_pk_bf16_f32 v101, v94, v95
	v_lshl_add_u64 v[102:103], v[98:99], 1, s[40:41]
	global_store_dwordx2 v[102:103], v[100:101], off
.LBB0_273:
	v_pk_fma_f32 v[90:91], v[90:91], 0.5, v[154:155] op_sel_hi:[1,0,1]
	v_pk_fma_f32 v[88:89], v[88:89], 0.5, v[152:153] op_sel_hi:[1,0,1]
	s_and_b64 vcc, exec, s[10:11]
	v_lshlrev_b64 v[98:99], 1, v[98:99]
	global_store_dwordx4 v[96:97], v[88:91], off offset:64 nt
	s_cbranch_vccnz .LBB0_275
	v_or_b32_e32 v102, 32, v98
	v_mov_b32_e32 v103, v99
	v_cvt_pk_bf16_f32 v100, v88, v89
	v_cvt_pk_bf16_f32 v101, v90, v91
	v_lshl_add_u64 v[102:103], s[40:41], 0, v[102:103]
	global_store_dwordx2 v[102:103], v[100:101], off
.LBB0_275:
	v_pk_fma_f32 v[86:87], v[86:87], 0.5, v[150:151] op_sel_hi:[1,0,1]
	v_pk_fma_f32 v[84:85], v[84:85], 0.5, v[148:149] op_sel_hi:[1,0,1]
	s_and_b64 vcc, exec, s[10:11]
	global_store_dwordx4 v[96:97], v[84:87], off offset:512 nt
	s_cbranch_vccnz .LBB0_277
	v_or_b32_e32 v102, 0x100, v98
	v_mov_b32_e32 v103, v99
	v_cvt_pk_bf16_f32 v100, v84, v85
	v_cvt_pk_bf16_f32 v101, v86, v87
	v_lshl_add_u64 v[102:103], s[40:41], 0, v[102:103]
	global_store_dwordx2 v[102:103], v[100:101], off
.LBB0_277:
	v_pk_fma_f32 v[82:83], v[82:83], 0.5, v[146:147] op_sel_hi:[1,0,1]
	v_pk_fma_f32 v[80:81], v[80:81], 0.5, v[144:145] op_sel_hi:[1,0,1]
	s_and_b64 vcc, exec, s[10:11]
	global_store_dwordx4 v[96:97], v[80:83], off offset:576 nt
	s_cbranch_vccnz .LBB0_279
	v_or_b32_e32 v98, 0x120, v98
	v_cvt_pk_bf16_f32 v96, v80, v81
	v_cvt_pk_bf16_f32 v97, v82, v83
	v_lshl_add_u64 v[98:99], s[40:41], 0, v[98:99]
	global_store_dwordx2 v[98:99], v[96:97], off

; __device__ __forceinline__ unsigned cvt_pk_bf16(float lo, float hi) { f32x2 v = {lo, hi}; bf16x2_t b = __builtin_convertvector(v, bf16x2_t); return __builtin_bit_cast(unsigned, b); }
;     __device__ __forceinline__ void operator()(const f32x4 (&acc)[2][2][4][2], const Unit& u, int wr, int wc, int fr, int fq) const {
;     ...
;             for (int m = 0; m < 4; ++m) { const int row = row0 + ai * HALF + m * 16; const size_t off = (size_t)row * DMODEL + col0; float sq = 0.f;
; #pragma unroll
;                 for (int bj = 0; bj < 2; ++bj)
; #pragma unroll
;                     for (int n = 0; n < 2; ++n) { const size_t o2 = off + bj * HALF + n * 16; const f32x4 o = bs[m][bj][n] + acc[ai][bj][m][n] * alpha;
;                         *(f32x4*)(out + o2) = o; sq += (o[0] * o[0] + o[1] * o[1]) + (o[2] * o[2] + o[3] * o[3]);
;                         if (outb) { u32x2 w; w.x = cvt_pk_bf16(o[0], o[1]); w.y = cvt_pk_bf16(o[2], o[3]); *(u32x2*)(outb + o2) = w; } }
.LBB0_281:
	s_or_b64 exec, exec, s[12:13]
	s_waitcnt lgkmcnt(0)
	v_lshlrev_b64 v[80:81], 11, v[206:207]
	v_lshl_add_u64 v[82:83], v[80:81], 0, v[200:201]
	v_pk_fma_f32 v[78:79], v[78:79], 0.5, v[142:143] op_sel_hi:[1,0,1]
	v_pk_fma_f32 v[76:77], v[76:77], 0.5, v[140:141] op_sel_hi:[1,0,1]
	v_lshl_add_u64 v[80:81], v[82:83], 2, s[56:57]
	s_and_b64 vcc, exec, s[10:11]
	global_store_dwordx4 v[80:81], v[76:79], off nt
	s_cbranch_vccnz .LBB0_283
	v_cvt_pk_bf16_f32 v84, v76, v77
	v_cvt_pk_bf16_f32 v85, v78, v79
	v_lshl_add_u64 v[86:87], v[82:83], 1, s[40:41]
	global_store_dwordx2 v[86:87], v[84:85], off
.LBB0_283:
	v_pk_fma_f32 v[74:75], v[74:75], 0.5, v[138:139] op_sel_hi:[1,0,1]
	v_pk_fma_f32 v[72:73], v[72:73], 0.5, v[136:137] op_sel_hi:[1,0,1]
	s_and_b64 vcc, exec, s[10:11]
	v_lshlrev_b64 v[82:83], 1, v[82:83]
	global_store_dwordx4 v[80:81], v[72:75], off offset:64 nt
	s_cbranch_vccnz .LBB0_285
	v_or_b32_e32 v86, 32, v82
	v_mov_b32_e32 v87, v83
	v_cvt_pk_bf16_f32 v84, v72, v73
	v_cvt_pk_bf16_f32 v85, v74, v75
	v_lshl_add_u64 v[86:87], s[40:41], 0, v[86:87]
	global_store_dwordx2 v[86:87], v[84:85], off
.LBB0_285:
	v_pk_fma_f32 v[70:71], v[70:71], 0.5, v[134:135] op_sel_hi:[1,0,1]
	v_pk_fma_f32 v[68:69], v[68:69], 0.5, v[132:133] op_sel_hi:[1,0,1]
	s_and_b64 vcc, exec, s[10:11]
	global_store_dwordx4 v[80:81], v[68:71], off offset:512 nt
	s_cbranch_vccnz .LBB0_287
	v_or_b32_e32 v86, 0x100, v82
	v_mov_b32_e32 v87, v83
	v_cvt_pk_bf16_f32 v84, v68, v69
	v_cvt_pk_bf16_f32 v85, v70, v71
	v_lshl_add_u64 v[86:87], s[40:41], 0, v[86:87]
	global_store_dwordx2 v[86:87], v[84:85], off
.LBB0_287:
	v_pk_fma_f32 v[66:67], v[66:67], 0.5, v[130:131] op_sel_hi:[1,0,1]
	v_pk_fma_f32 v[64:65], v[64:65], 0.5, v[128:129] op_sel_hi:[1,0,1]
	s_and_b64 vcc, exec, s[10:11]
	global_store_dwordx4 v[80:81], v[64:67], off offset:576 nt
	s_cbranch_vccnz .LBB0_289
	v_or_b32_e32 v82, 0x120, v82
	v_cvt_pk_bf16_f32 v80, v64, v65
	v_cvt_pk_bf16_f32 v81, v66, v67
	v_lshl_add_u64 v[82:83], s[40:41], 0, v[82:83]
	global_store_dwordx2 v[82:83], v[80:81], off

; __device__ __forceinline__ unsigned cvt_pk_bf16(float lo, float hi) { f32x2 v = {lo, hi}; bf16x2_t b = __builtin_convertvector(v, bf16x2_t); return __builtin_bit_cast(unsigned, b); }
;     __device__ __forceinline__ void operator()(const f32x4 (&acc)[2][2][4][2], const Unit& u, int wr, int wc, int fr, int fq) const {
;     ...
;         for (int ai = 0; ai < 2; ++ai) {
;             f32x4 bs[4][2][2];
; #pragma unroll
;             for (int m = 0; m < 4; ++m)
; #pragma unroll
;                 for (int bj = 0; bj < 2; ++bj)
; #pragma unroll
;                     for (int n = 0; n < 2; ++n) bs[m][bj][n] = *(const f32x4*)(base + (size_t)(row0 + ai * HALF + m * 16) * DMODEL + col0 + bj * HALF + n * 16);
; #pragma unroll
;             for (int m = 0; m < 4; ++m) { const int row = row0 + ai * HALF + m * 16; const size_t off = (size_t)row * DMODEL + col0; float sq = 0.f;
; #pragma unroll
;                 for (int bj = 0; bj < 2; ++bj)
; #pragma unroll
;                     for (int n = 0; n < 2; ++n) { const size_t o2 = off + bj * HALF + n * 16; const f32x4 o = bs[m][bj][n] + acc[ai][bj][m][n] * alpha;
;                         *(f32x4*)(out + o2) = o; sq += (o[0] * o[0] + o[1] * o[1]) + (o[2] * o[2] + o[3] * o[3]);
;                         if (outb) { u32x2 w; w.x = cvt_pk_bf16(o[0], o[1]); w.y = cvt_pk_bf16(o[2], o[3]); *(u32x2*)(outb + o2) = w; } }
.LBB0_291:
	s_or_b64 exec, exec, s[12:13]
	v_add_u32_e32 v130, 0x80, v204
	v_ashrrev_i32_e32 v131, 31, v130
	s_waitcnt lgkmcnt(0)
	v_lshlrev_b64 v[64:65], 13, v[130:131]
	v_add_u32_e32 v128, 0x90, v204
	v_lshl_add_u64 v[64:65], v[202:203], 0, v[64:65]
	v_ashrrev_i32_e32 v129, 31, v128
	global_load_dwordx4 v[136:139], v[64:65], off nt
	global_load_dwordx4 v[120:123], v[64:65], off offset:64 nt
	global_load_dwordx4 v[116:119], v[64:65], off offset:512 nt
	global_load_dwordx4 v[112:115], v[64:65], off offset:576 nt
	v_lshlrev_b64 v[64:65], 13, v[128:129]
	v_add_u32_e32 v126, 0xa0, v204
	v_lshl_add_u64 v[64:65], v[202:203], 0, v[64:65]
	v_ashrrev_i32_e32 v127, 31, v126
	global_load_dwordx4 v[108:111], v[64:65], off nt
	global_load_dwordx4 v[104:107], v[64:65], off offset:64 nt
	global_load_dwordx4 v[100:103], v[64:65], off offset:512 nt
	global_load_dwordx4 v[96:99], v[64:65], off offset:576 nt
	v_lshlrev_b64 v[64:65], 13, v[126:127]
	v_add_u32_e32 v124, 0xb0, v204
	v_lshl_add_u64 v[64:65], v[202:203], 0, v[64:65]
	v_ashrrev_i32_e32 v125, 31, v124
	global_load_dwordx4 v[92:95], v[64:65], off nt
	global_load_dwordx4 v[88:91], v[64:65], off offset:64 nt
	global_load_dwordx4 v[84:87], v[64:65], off offset:512 nt
	global_load_dwordx4 v[80:83], v[64:65], off offset:576 nt
	v_lshlrev_b64 v[64:65], 13, v[124:125]
	v_lshl_add_u64 v[64:65], v[202:203], 0, v[64:65]
	global_load_dwordx4 v[76:79], v[64:65], off nt
	global_load_dwordx4 v[72:75], v[64:65], off offset:64 nt
	global_load_dwordx4 v[68:71], v[64:65], off offset:512 nt
	s_nop 0
	global_load_dwordx4 v[64:67], v[64:65], off offset:576 nt
	v_lshlrev_b64 v[132:133], 11, v[130:131]
	v_lshl_add_u64 v[134:135], v[132:133], 0, v[200:201]
	v_lshl_add_u64 v[132:133], v[134:135], 2, s[56:57]
	s_and_b64 vcc, exec, s[10:11]
	s_waitcnt vmcnt(15)
	v_pk_fma_f32 v[62:63], v[62:63], 0.5, v[138:139] op_sel_hi:[1,0,1]
	v_pk_fma_f32 v[60:61], v[60:61], 0.5, v[136:137] op_sel_hi:[1,0,1]
	global_store_dwordx4 v[132:133], v[60:63], off nt
	s_cbranch_vccnz .LBB0_293
	v_cvt_pk_bf16_f32 v136, v60, v61
	v_cvt_pk_bf16_f32 v137, v62, v63
	v_lshl_add_u64 v[138:139], v[134:135], 1, s[40:41]
	global_store_dwordx2 v[138:139], v[136:137], off
.LBB0_293:
	s_waitcnt vmcnt(15)
	v_pk_fma_f32 v[58:59], v[58:59], 0.5, v[122:123] op_sel_hi:[1,0,1]
	v_pk_fma_f32 v[56:57], v[56:57], 0.5, v[120:121] op_sel_hi:[1,0,1]
	s_and_b64 vcc, exec, s[10:11]
	v_lshlrev_b64 v[120:121], 1, v[134:135]
	global_store_dwordx4 v[132:133], v[56:59], off offset:64 nt
	s_cbranch_vccnz .LBB0_295
	v_or_b32_e32 v134, 32, v120
	v_mov_b32_e32 v135, v121
	v_cvt_pk_bf16_f32 v122, v56, v57
	v_cvt_pk_bf16_f32 v123, v58, v59
	v_lshl_add_u64 v[134:135], s[40:41], 0, v[134:135]
	global_store_dwordx2 v[134:135], v[122:123], off
.LBB0_295:
	s_waitcnt vmcnt(15)
	v_pk_fma_f32 v[54:55], v[54:55], 0.5, v[118:119] op_sel_hi:[1,0,1]
	v_pk_fma_f32 v[52:53], v[52:53], 0.5, v[116:117] op_sel_hi:[1,0,1]
	s_and_b64 vcc, exec, s[10:11]
	global_store_dwordx4 v[132:133], v[52:55], off offset:512 nt
	s_cbranch_vccnz .LBB0_297
	v_or_b32_e32 v118, 0x100, v120
	v_mov_b32_e32 v119, v121
	v_cvt_pk_bf16_f32 v116, v52, v53
	v_cvt_pk_bf16_f32 v117, v54, v55
	v_lshl_add_u64 v[118:119], s[40:41], 0, v[118:119]
	global_store_dwordx2 v[118:119], v[116:117], off
.LBB0_297:
	s_waitcnt vmcnt(15)
	v_pk_fma_f32 v[50:51], v[50:51], 0.5, v[114:115] op_sel_hi:[1,0,1]
	v_pk_fma_f32 v[48:49], v[48:49], 0.5, v[112:113] op_sel_hi:[1,0,1]
	s_and_b64 vcc, exec, s[10:11]
	global_store_dwordx4 v[132:133], v[48:51], off offset:576 nt
	s_cbranch_vccnz .LBB0_299
	v_or_b32_e32 v120, 0x120, v120
	v_cvt_pk_bf16_f32 v112, v48, v49
	v_cvt_pk_bf16_f32 v113, v50, v51
	v_lshl_add_u64 v[114:115], s[40:41], 0, v[120:121]
	global_store_dwordx2 v[114:115], v[112:113], off

; __device__ __forceinline__ unsigned cvt_pk_bf16(float lo, float hi) { f32x2 v = {lo, hi}; bf16x2_t b = __builtin_convertvector(v, bf16x2_t); return __builtin_bit_cast(unsigned, b); }
;     __device__ __forceinline__ void operator()(const f32x4 (&acc)[2][2][4][2], const Unit& u, int wr, int wc, int fr, int fq) const {
;     ...
;             for (int m = 0; m < 4; ++m) { const int row = row0 + ai * HALF + m * 16; const size_t off = (size_t)row * DMODEL + col0; float sq = 0.f;
; #pragma unroll
;                 for (int bj = 0; bj < 2; ++bj)
; #pragma unroll
;                     for (int n = 0; n < 2; ++n) { const size_t o2 = off + bj * HALF + n * 16; const f32x4 o = bs[m][bj][n] + acc[ai][bj][m][n] * alpha;
;                         *(f32x4*)(out + o2) = o; sq += (o[0] * o[0] + o[1] * o[1]) + (o[2] * o[2] + o[3] * o[3]);
;                         if (outb) { u32x2 w; w.x = cvt_pk_bf16(o[0], o[1]); w.y = cvt_pk_bf16(o[2], o[3]); *(u32x2*)(outb + o2) = w; } }
.LBB0_301:
	s_or_b64 exec, exec, s[12:13]
	s_waitcnt lgkmcnt(0)
	v_lshlrev_b64 v[48:49], 11, v[128:129]
	v_lshl_add_u64 v[50:51], v[48:49], 0, v[200:201]
	s_waitcnt vmcnt(15)
	v_pk_fma_f32 v[46:47], v[46:47], 0.5, v[110:111] op_sel_hi:[1,0,1]
	v_pk_fma_f32 v[44:45], v[44:45], 0.5, v[108:109] op_sel_hi:[1,0,1]
	v_lshl_add_u64 v[48:49], v[50:51], 2, s[56:57]
	s_and_b64 vcc, exec, s[10:11]
	global_store_dwordx4 v[48:49], v[44:47], off nt
	s_cbranch_vccnz .LBB0_303
	v_cvt_pk_bf16_f32 v52, v44, v45
	v_cvt_pk_bf16_f32 v53, v46, v47
	v_lshl_add_u64 v[54:55], v[50:51], 1, s[40:41]
	global_store_dwordx2 v[54:55], v[52:53], off
.LBB0_303:
	s_waitcnt vmcnt(15)
	v_pk_fma_f32 v[42:43], v[42:43], 0.5, v[106:107] op_sel_hi:[1,0,1]
	v_pk_fma_f32 v[40:41], v[40:41], 0.5, v[104:105] op_sel_hi:[1,0,1]
	s_and_b64 vcc, exec, s[10:11]
	v_lshlrev_b64 v[50:51], 1, v[50:51]
	global_store_dwordx4 v[48:49], v[40:43], off offset:64 nt
	s_cbranch_vccnz .LBB0_305
	v_or_b32_e32 v54, 32, v50
	v_mov_b32_e32 v55, v51
	v_cvt_pk_bf16_f32 v52, v40, v41
	v_cvt_pk_bf16_f32 v53, v42, v43
	v_lshl_add_u64 v[54:55], s[40:41], 0, v[54:55]
	global_store_dwordx2 v[54:55], v[52:53], off
.LBB0_305:
	s_waitcnt vmcnt(15)
	v_pk_fma_f32 v[38:39], v[38:39], 0.5, v[102:103] op_sel_hi:[1,0,1]
	v_pk_fma_f32 v[36:37], v[36:37], 0.5, v[100:101] op_sel_hi:[1,0,1]
	s_and_b64 vcc, exec, s[10:11]
	global_store_dwordx4 v[48:49], v[36:39], off offset:512 nt
	s_cbranch_vccnz .LBB0_307
	v_or_b32_e32 v54, 0x100, v50
	v_mov_b32_e32 v55, v51
	v_cvt_pk_bf16_f32 v52, v36, v37
	v_cvt_pk_bf16_f32 v53, v38, v39
	v_lshl_add_u64 v[54:55], s[40:41], 0, v[54:55]
	global_store_dwordx2 v[54:55], v[52:53], off
.LBB0_307:
	s_waitcnt vmcnt(15)
	v_pk_fma_f32 v[34:35], v[34:35], 0.5, v[98:99] op_sel_hi:[1,0,1]
	v_pk_fma_f32 v[32:33], v[32:33], 0.5, v[96:97] op_sel_hi:[1,0,1]
	s_and_b64 vcc, exec, s[10:11]
	global_store_dwordx4 v[48:49], v[32:35], off offset:576 nt
	s_cbranch_vccnz .LBB0_309
	v_or_b32_e32 v50, 0x120, v50
	v_cvt_pk_bf16_f32 v48, v32, v33
	v_cvt_pk_bf16_f32 v49, v34, v35
	v_lshl_add_u64 v[50:51], s[40:41], 0, v[50:51]
	global_store_dwordx2 v[50:51], v[48:49], off

; __device__ __forceinline__ unsigned cvt_pk_bf16(float lo, float hi) { f32x2 v = {lo, hi}; bf16x2_t b = __builtin_convertvector(v, bf16x2_t); return __builtin_bit_cast(unsigned, b); }
;     __device__ __forceinline__ void operator()(const f32x4 (&acc)[2][2][4][2], const Unit& u, int wr, int wc, int fr, int fq) const {
;     ...
;             for (int m = 0; m < 4; ++m) { const int row = row0 + ai * HALF + m * 16; const size_t off = (size_t)row * DMODEL + col0; float sq = 0.f;
; #pragma unroll
;                 for (int bj = 0; bj < 2; ++bj)
; #pragma unroll
;                     for (int n = 0; n < 2; ++n) { const size_t o2 = off + bj * HALF + n * 16; const f32x4 o = bs[m][bj][n] + acc[ai][bj][m][n] * alpha;
;                         *(f32x4*)(out + o2) = o; sq += (o[0] * o[0] + o[1] * o[1]) + (o[2] * o[2] + o[3] * o[3]);
;                         if (outb) { u32x2 w; w.x = cvt_pk_bf16(o[0], o[1]); w.y = cvt_pk_bf16(o[2], o[3]); *(u32x2*)(outb + o2) = w; } }
.LBB0_311:
	s_or_b64 exec, exec, s[12:13]
	s_waitcnt lgkmcnt(0)
	v_lshlrev_b64 v[32:33], 11, v[126:127]
	v_lshl_add_u64 v[34:35], v[32:33], 0, v[200:201]
	s_waitcnt vmcnt(15)
	v_pk_fma_f32 v[30:31], v[30:31], 0.5, v[94:95] op_sel_hi:[1,0,1]
	v_pk_fma_f32 v[28:29], v[28:29], 0.5, v[92:93] op_sel_hi:[1,0,1]
	v_lshl_add_u64 v[32:33], v[34:35], 2, s[56:57]
	s_and_b64 vcc, exec, s[10:11]
	global_store_dwordx4 v[32:33], v[28:31], off nt
	s_cbranch_vccnz .LBB0_313
	v_cvt_pk_bf16_f32 v36, v28, v29
	v_cvt_pk_bf16_f32 v37, v30, v31
	v_lshl_add_u64 v[38:39], v[34:35], 1, s[40:41]
	global_store_dwordx2 v[38:39], v[36:37], off
.LBB0_313:
	s_waitcnt vmcnt(15)
	v_pk_fma_f32 v[26:27], v[26:27], 0.5, v[90:91] op_sel_hi:[1,0,1]
	v_pk_fma_f32 v[24:25], v[24:25], 0.5, v[88:89] op_sel_hi:[1,0,1]
	s_and_b64 vcc, exec, s[10:11]
	v_lshlrev_b64 v[34:35], 1, v[34:35]
	global_store_dwordx4 v[32:33], v[24:27], off offset:64 nt
	s_cbranch_vccnz .LBB0_315
	v_or_b32_e32 v38, 32, v34
	v_mov_b32_e32 v39, v35
	v_cvt_pk_bf16_f32 v36, v24, v25
	v_cvt_pk_bf16_f32 v37, v26, v27
	v_lshl_add_u64 v[38:39], s[40:41], 0, v[38:39]
	global_store_dwordx2 v[38:39], v[36:37], off
.LBB0_315:
	s_waitcnt vmcnt(15)
	v_pk_fma_f32 v[22:23], v[22:23], 0.5, v[86:87] op_sel_hi:[1,0,1]
	v_pk_fma_f32 v[20:21], v[20:21], 0.5, v[84:85] op_sel_hi:[1,0,1]
	s_and_b64 vcc, exec, s[10:11]
	global_store_dwordx4 v[32:33], v[20:23], off offset:512 nt
	s_cbranch_vccnz .LBB0_317
	v_or_b32_e32 v38, 0x100, v34
	v_mov_b32_e32 v39, v35
	v_cvt_pk_bf16_f32 v36, v20, v21
	v_cvt_pk_bf16_f32 v37, v22, v23
	v_lshl_add_u64 v[38:39], s[40:41], 0, v[38:39]
	global_store_dwordx2 v[38:39], v[36:37], off
.LBB0_317:
	s_waitcnt vmcnt(15)
	v_pk_fma_f32 v[18:19], v[18:19], 0.5, v[82:83] op_sel_hi:[1,0,1]
	v_pk_fma_f32 v[16:17], v[16:17], 0.5, v[80:81] op_sel_hi:[1,0,1]
	s_and_b64 vcc, exec, s[10:11]
	global_store_dwordx4 v[32:33], v[16:19], off offset:576 nt
	s_cbranch_vccnz .LBB0_319
	v_or_b32_e32 v34, 0x120, v34
	v_cvt_pk_bf16_f32 v32, v16, v17
	v_cvt_pk_bf16_f32 v33, v18, v19
	v_lshl_add_u64 v[34:35], s[40:41], 0, v[34:35]
	global_store_dwordx2 v[34:35], v[32:33], off

; __device__ __forceinline__ unsigned cvt_pk_bf16(float lo, float hi) { f32x2 v = {lo, hi}; bf16x2_t b = __builtin_convertvector(v, bf16x2_t); return __builtin_bit_cast(unsigned, b); }
;     __device__ __forceinline__ void operator()(const f32x4 (&acc)[2][2][4][2], const Unit& u, int wr, int wc, int fr, int fq) const {
;     ...
;             for (int m = 0; m < 4; ++m) { const int row = row0 + ai * HALF + m * 16; const size_t off = (size_t)row * DMODEL + col0; float sq = 0.f;
; #pragma unroll
;                 for (int bj = 0; bj < 2; ++bj)
; #pragma unroll
;                     for (int n = 0; n < 2; ++n) { const size_t o2 = off + bj * HALF + n * 16; const f32x4 o = bs[m][bj][n] + acc[ai][bj][m][n] * alpha;
;                         *(f32x4*)(out + o2) = o; sq += (o[0] * o[0] + o[1] * o[1]) + (o[2] * o[2] + o[3] * o[3]);
;                         if (outb) { u32x2 w; w.x = cvt_pk_bf16(o[0], o[1]); w.y = cvt_pk_bf16(o[2], o[3]); *(u32x2*)(outb + o2) = w; } }
.LBB0_321:
	s_or_b64 exec, exec, s[12:13]
	s_waitcnt lgkmcnt(0)
	v_lshlrev_b64 v[16:17], 11, v[124:125]
	v_lshl_add_u64 v[18:19], v[16:17], 0, v[200:201]
	s_waitcnt vmcnt(15)
	v_pk_fma_f32 v[14:15], v[14:15], 0.5, v[78:79] op_sel_hi:[1,0,1]
	v_pk_fma_f32 v[12:13], v[12:13], 0.5, v[76:77] op_sel_hi:[1,0,1]
	v_lshl_add_u64 v[16:17], v[18:19], 2, s[56:57]
	s_and_b64 vcc, exec, s[10:11]
	global_store_dwordx4 v[16:17], v[12:15], off nt
	s_cbranch_vccnz .LBB0_323
	v_cvt_pk_bf16_f32 v20, v12, v13
	v_cvt_pk_bf16_f32 v21, v14, v15
	v_lshl_add_u64 v[22:23], v[18:19], 1, s[40:41]
	global_store_dwordx2 v[22:23], v[20:21], off
.LBB0_323:
	s_waitcnt vmcnt(15)
	v_pk_fma_f32 v[10:11], v[10:11], 0.5, v[74:75] op_sel_hi:[1,0,1]
	v_pk_fma_f32 v[8:9], v[8:9], 0.5, v[72:73] op_sel_hi:[1,0,1]
	s_and_b64 vcc, exec, s[10:11]
	v_lshlrev_b64 v[18:19], 1, v[18:19]
	global_store_dwordx4 v[16:17], v[8:11], off offset:64 nt
	s_cbranch_vccnz .LBB0_325
	v_or_b32_e32 v22, 32, v18
	v_mov_b32_e32 v23, v19
	v_cvt_pk_bf16_f32 v20, v8, v9
	v_cvt_pk_bf16_f32 v21, v10, v11
	v_lshl_add_u64 v[22:23], s[40:41], 0, v[22:23]
	global_store_dwordx2 v[22:23], v[20:21], off
.LBB0_325:
	s_waitcnt vmcnt(15)
	v_pk_fma_f32 v[6:7], v[6:7], 0.5, v[70:71] op_sel_hi:[1,0,1]
	v_pk_fma_f32 v[4:5], v[4:5], 0.5, v[68:69] op_sel_hi:[1,0,1]
	s_and_b64 vcc, exec, s[10:11]
	global_store_dwordx4 v[16:17], v[4:7], off offset:512 nt
	s_cbranch_vccnz .LBB0_327
	v_or_b32_e32 v22, 0x100, v18
	v_mov_b32_e32 v23, v19
	v_cvt_pk_bf16_f32 v20, v4, v5
	v_cvt_pk_bf16_f32 v21, v6, v7
	v_lshl_add_u64 v[22:23], s[40:41], 0, v[22:23]
	global_store_dwordx2 v[22:23], v[20:21], off
.LBB0_327:
	s_waitcnt vmcnt(15)
	v_pk_fma_f32 v[2:3], v[2:3], 0.5, v[66:67] op_sel_hi:[1,0,1]
	v_pk_fma_f32 v[0:1], v[0:1], 0.5, v[64:65] op_sel_hi:[1,0,1]
	s_and_b64 vcc, exec, s[10:11]
	global_store_dwordx4 v[16:17], v[0:3], off offset:576 nt
	s_cbranch_vccnz .LBB0_329
	v_or_b32_e32 v18, 0x120, v18
	v_cvt_pk_bf16_f32 v16, v0, v1
	v_cvt_pk_bf16_f32 v17, v2, v3
	v_lshl_add_u64 v[18:19], s[40:41], 0, v[18:19]
	global_store_dwordx2 v[18:19], v[16:17], off

; __device__ __forceinline__ unsigned cvt_pk_bf16(float lo, float hi) { f32x2 v = {lo, hi}; bf16x2_t b = __builtin_convertvector(v, bf16x2_t); return __builtin_bit_cast(unsigned, b); }
;     __device__ __forceinline__ void operator()(const f32x4 (&acc)[2][2][4][2], const Unit& u, int wr, int wc, int fr, int fq) const {
;     ...
;                     for (int n = 0; n < 2; ++n) bs[m][bj][n] = *(const f32x4*)(base + (size_t)(row0 + ai * HALF + m * 16) * DMODEL + col0 + bj * HALF + n * 16);
; #pragma unroll
;             for (int m = 0; m < 4; ++m) { const int row = row0 + ai * HALF + m * 16; const size_t off = (size_t)row * DMODEL + col0; float sq = 0.f;
; #pragma unroll
;                 for (int bj = 0; bj < 2; ++bj)
; #pragma unroll
;                     for (int n = 0; n < 2; ++n) { const size_t o2 = off + bj * HALF + n * 16; const f32x4 o = bs[m][bj][n] + acc[ai][bj][m][n] * alpha;
;                         *(f32x4*)(out + o2) = o; sq += (o[0] * o[0] + o[1] * o[1]) + (o[2] * o[2] + o[3] * o[3]);
;                         if (outb) { u32x2 w; w.x = cvt_pk_bf16(o[0], o[1]); w.y = cvt_pk_bf16(o[2], o[3]); *(u32x2*)(outb + o2) = w; } }
.LBB0_879:
	v_lshl_add_u32 v204, s10, 8, v225
	v_lshl_or_b32 v200, s16, 8, v227
	v_ashrrev_i32_e32 v201, 31, v200
	v_ashrrev_i32_e32 v205, 31, v204
	v_or_b32_e32 v214, 16, v204
	v_lshl_add_u64 v[202:203], v[200:201], 2, s[56:57]
	v_lshlrev_b64 v[128:129], 13, v[204:205]
	v_ashrrev_i32_e32 v215, 31, v214
	v_or_b32_e32 v210, 32, v204
	v_lshl_add_u64 v[218:219], v[202:203], 0, v[128:129]
	v_lshlrev_b64 v[128:129], 13, v[214:215]
	v_ashrrev_i32_e32 v211, 31, v210
	v_or_b32_e32 v206, 48, v204
	v_lshl_add_u64 v[216:217], v[202:203], 0, v[128:129]
	v_lshlrev_b64 v[128:129], 13, v[210:211]
	v_ashrrev_i32_e32 v207, 31, v206
	v_lshl_add_u64 v[212:213], v[202:203], 0, v[128:129]
	v_lshlrev_b64 v[128:129], 13, v[206:207]
	v_lshl_add_u64 v[208:209], v[202:203], 0, v[128:129]
	global_load_dwordx4 v[232:235], v[218:219], off nt
	global_load_dwordx4 v[184:187], v[218:219], off offset:64 nt
	global_load_dwordx4 v[180:183], v[218:219], off offset:512 nt
	global_load_dwordx4 v[176:179], v[218:219], off offset:576 nt
	global_load_dwordx4 v[172:175], v[216:217], off nt
	global_load_dwordx4 v[168:171], v[216:217], off offset:64 nt
	global_load_dwordx4 v[164:167], v[216:217], off offset:512 nt
	global_load_dwordx4 v[160:163], v[216:217], off offset:576 nt
	global_load_dwordx4 v[156:159], v[212:213], off nt
	global_load_dwordx4 v[152:155], v[212:213], off offset:64 nt
	global_load_dwordx4 v[148:151], v[212:213], off offset:512 nt
	global_load_dwordx4 v[144:147], v[212:213], off offset:576 nt
	global_load_dwordx4 v[140:143], v[208:209], off nt
	global_load_dwordx4 v[136:139], v[208:209], off offset:64 nt
	global_load_dwordx4 v[132:135], v[208:209], off offset:512 nt
	global_load_dwordx4 v[128:131], v[208:209], off offset:576 nt
	v_cndmask_b32_e64 v220, 0, 1, s[24:25]
	v_cmp_ne_u32_e64 s[10:11], 1, v220
	v_lshlrev_b64 v[220:221], 11, v[204:205]
	v_lshl_add_u64 v[220:221], v[220:221], 0, v[200:201]
	s_andn2_b64 vcc, exec, s[24:25]
	s_waitcnt vmcnt(0)
	v_pk_add_f32 v[126:127], v[126:127], v[234:235]
	v_pk_add_f32 v[124:125], v[124:125], v[232:233]
	global_store_dwordx4 v[218:219], v[124:127], off nt
	s_cbranch_vccnz .LBB0_881
	v_cvt_pk_bf16_f32 v232, v124, v125
	v_cvt_pk_bf16_f32 v233, v126, v127
	v_lshl_add_u64 v[234:235], v[220:221], 1, s[40:41]
	global_store_dwordx2 v[234:235], v[232:233], off
.LBB0_881:
	v_pk_add_f32 v[122:123], v[122:123], v[186:187]
	v_pk_add_f32 v[120:121], v[120:121], v[184:185]
	s_and_b64 vcc, exec, s[10:11]
	v_lshlrev_b64 v[184:185], 1, v[220:221]
	global_store_dwordx4 v[218:219], v[120:123], off offset:64 nt
	s_cbranch_vccnz .LBB0_883
	v_or_b32_e32 v220, 32, v184
	v_mov_b32_e32 v221, v185
	v_cvt_pk_bf16_f32 v186, v120, v121
	v_cvt_pk_bf16_f32 v187, v122, v123
	v_lshl_add_u64 v[220:221], s[40:41], 0, v[220:221]
	global_store_dwordx2 v[220:221], v[186:187], off
.LBB0_883:
	v_pk_add_f32 v[118:119], v[118:119], v[182:183]
	v_pk_add_f32 v[116:117], v[116:117], v[180:181]
	s_and_b64 vcc, exec, s[10:11]
	global_store_dwordx4 v[218:219], v[116:119], off offset:512 nt
	s_cbranch_vccnz .LBB0_885
	v_or_b32_e32 v182, 0x100, v184
	v_mov_b32_e32 v183, v185
	v_cvt_pk_bf16_f32 v180, v116, v117
	v_cvt_pk_bf16_f32 v181, v118, v119
	v_lshl_add_u64 v[182:183], s[40:41], 0, v[182:183]
	global_store_dwordx2 v[182:183], v[180:181], off
.LBB0_885:
	v_pk_add_f32 v[114:115], v[114:115], v[178:179]
	v_pk_add_f32 v[112:113], v[112:113], v[176:177]
	s_and_b64 vcc, exec, s[10:11]
	global_store_dwordx4 v[218:219], v[112:115], off offset:576 nt
	s_cbranch_vccnz .LBB0_887
	v_or_b32_e32 v184, 0x120, v184
	v_cvt_pk_bf16_f32 v176, v112, v113
	v_cvt_pk_bf16_f32 v177, v114, v115
	v_lshl_add_u64 v[178:179], s[40:41], 0, v[184:185]
	global_store_dwordx2 v[178:179], v[176:177], off

; __device__ __forceinline__ unsigned cvt_pk_bf16(float lo, float hi) { f32x2 v = {lo, hi}; bf16x2_t b = __builtin_convertvector(v, bf16x2_t); return __builtin_bit_cast(unsigned, b); }
;     __device__ __forceinline__ void operator()(const f32x4 (&acc)[2][2][4][2], const Unit& u, int wr, int wc, int fr, int fq) const {
;     ...
;             for (int m = 0; m < 4; ++m) { const int row = row0 + ai * HALF + m * 16; const size_t off = (size_t)row * DMODEL + col0; float sq = 0.f;
; #pragma unroll
;                 for (int bj = 0; bj < 2; ++bj)
; #pragma unroll
;                     for (int n = 0; n < 2; ++n) { const size_t o2 = off + bj * HALF + n * 16; const f32x4 o = bs[m][bj][n] + acc[ai][bj][m][n] * alpha;
;                         *(f32x4*)(out + o2) = o; sq += (o[0] * o[0] + o[1] * o[1]) + (o[2] * o[2] + o[3] * o[3]);
;                         if (outb) { u32x2 w; w.x = cvt_pk_bf16(o[0], o[1]); w.y = cvt_pk_bf16(o[2], o[3]); *(u32x2*)(outb + o2) = w; } }
.LBB0_889:
	s_or_b64 exec, exec, s[12:13]
	s_waitcnt lgkmcnt(0)
	v_lshlrev_b64 v[112:113], 11, v[214:215]
	v_lshl_add_u64 v[112:113], v[112:113], 0, v[200:201]
	v_pk_add_f32 v[110:111], v[110:111], v[174:175]
	v_pk_add_f32 v[108:109], v[108:109], v[172:173]
	s_and_b64 vcc, exec, s[10:11]
	global_store_dwordx4 v[216:217], v[108:111], off nt
	s_cbranch_vccnz .LBB0_891
	v_cvt_pk_bf16_f32 v114, v108, v109
	v_cvt_pk_bf16_f32 v115, v110, v111
	v_lshl_add_u64 v[116:117], v[112:113], 1, s[40:41]
	global_store_dwordx2 v[116:117], v[114:115], off
.LBB0_891:
	v_pk_add_f32 v[106:107], v[106:107], v[170:171]
	v_pk_add_f32 v[104:105], v[104:105], v[168:169]
	s_and_b64 vcc, exec, s[10:11]
	v_lshlrev_b64 v[112:113], 1, v[112:113]
	global_store_dwordx4 v[216:217], v[104:107], off offset:64 nt
	s_cbranch_vccnz .LBB0_893
	v_or_b32_e32 v116, 32, v112
	v_mov_b32_e32 v117, v113
	v_cvt_pk_bf16_f32 v114, v104, v105
	v_cvt_pk_bf16_f32 v115, v106, v107
	v_lshl_add_u64 v[116:117], s[40:41], 0, v[116:117]
	global_store_dwordx2 v[116:117], v[114:115], off
.LBB0_893:
	v_pk_add_f32 v[102:103], v[102:103], v[166:167]
	v_pk_add_f32 v[100:101], v[100:101], v[164:165]
	s_and_b64 vcc, exec, s[10:11]
	global_store_dwordx4 v[216:217], v[100:103], off offset:512 nt
	s_cbranch_vccnz .LBB0_895
	v_or_b32_e32 v116, 0x100, v112
	v_mov_b32_e32 v117, v113
	v_cvt_pk_bf16_f32 v114, v100, v101
	v_cvt_pk_bf16_f32 v115, v102, v103
	v_lshl_add_u64 v[116:117], s[40:41], 0, v[116:117]
	global_store_dwordx2 v[116:117], v[114:115], off
.LBB0_895:
	v_pk_add_f32 v[98:99], v[98:99], v[162:163]
	v_pk_add_f32 v[96:97], v[96:97], v[160:161]
	s_and_b64 vcc, exec, s[10:11]
	global_store_dwordx4 v[216:217], v[96:99], off offset:576 nt
	s_cbranch_vccnz .LBB0_897
	v_or_b32_e32 v112, 0x120, v112
	v_cvt_pk_bf16_f32 v114, v96, v97
	v_cvt_pk_bf16_f32 v115, v98, v99
	v_lshl_add_u64 v[112:113], s[40:41], 0, v[112:113]
	global_store_dwordx2 v[112:113], v[114:115], off

; __device__ __forceinline__ unsigned cvt_pk_bf16(float lo, float hi) { f32x2 v = {lo, hi}; bf16x2_t b = __builtin_convertvector(v, bf16x2_t); return __builtin_bit_cast(unsigned, b); }
;     __device__ __forceinline__ void operator()(const f32x4 (&acc)[2][2][4][2], const Unit& u, int wr, int wc, int fr, int fq) const {
;     ...
;             for (int m = 0; m < 4; ++m) { const int row = row0 + ai * HALF + m * 16; const size_t off = (size_t)row * DMODEL + col0; float sq = 0.f;
; #pragma unroll
;                 for (int bj = 0; bj < 2; ++bj)
; #pragma unroll
;                     for (int n = 0; n < 2; ++n) { const size_t o2 = off + bj * HALF + n * 16; const f32x4 o = bs[m][bj][n] + acc[ai][bj][m][n] * alpha;
;                         *(f32x4*)(out + o2) = o; sq += (o[0] * o[0] + o[1] * o[1]) + (o[2] * o[2] + o[3] * o[3]);
;                         if (outb) { u32x2 w; w.x = cvt_pk_bf16(o[0], o[1]); w.y = cvt_pk_bf16(o[2], o[3]); *(u32x2*)(outb + o2) = w; } }
.LBB0_899:
	s_or_b64 exec, exec, s[12:13]
	s_waitcnt lgkmcnt(0)
	v_lshlrev_b64 v[96:97], 11, v[210:211]
	v_lshl_add_u64 v[96:97], v[96:97], 0, v[200:201]
	v_pk_add_f32 v[94:95], v[94:95], v[158:159]
	v_pk_add_f32 v[92:93], v[92:93], v[156:157]
	s_and_b64 vcc, exec, s[10:11]
	global_store_dwordx4 v[212:213], v[92:95], off nt
	s_cbranch_vccnz .LBB0_901
	v_cvt_pk_bf16_f32 v98, v92, v93
	v_cvt_pk_bf16_f32 v99, v94, v95
	v_lshl_add_u64 v[100:101], v[96:97], 1, s[40:41]
	global_store_dwordx2 v[100:101], v[98:99], off
.LBB0_901:
	v_pk_add_f32 v[90:91], v[90:91], v[154:155]
	v_pk_add_f32 v[88:89], v[88:89], v[152:153]
	s_and_b64 vcc, exec, s[10:11]
	v_lshlrev_b64 v[96:97], 1, v[96:97]
	global_store_dwordx4 v[212:213], v[88:91], off offset:64 nt
	s_cbranch_vccnz .LBB0_903
	v_or_b32_e32 v100, 32, v96
	v_mov_b32_e32 v101, v97
	v_cvt_pk_bf16_f32 v98, v88, v89
	v_cvt_pk_bf16_f32 v99, v90, v91
	v_lshl_add_u64 v[100:101], s[40:41], 0, v[100:101]
	global_store_dwordx2 v[100:101], v[98:99], off
.LBB0_903:
	v_pk_add_f32 v[86:87], v[86:87], v[150:151]
	v_pk_add_f32 v[84:85], v[84:85], v[148:149]
	s_and_b64 vcc, exec, s[10:11]
	global_store_dwordx4 v[212:213], v[84:87], off offset:512 nt
	s_cbranch_vccnz .LBB0_905
	v_or_b32_e32 v100, 0x100, v96
	v_mov_b32_e32 v101, v97
	v_cvt_pk_bf16_f32 v98, v84, v85
	v_cvt_pk_bf16_f32 v99, v86, v87
	v_lshl_add_u64 v[100:101], s[40:41], 0, v[100:101]
	global_store_dwordx2 v[100:101], v[98:99], off
.LBB0_905:
	v_pk_add_f32 v[82:83], v[82:83], v[146:147]
	v_pk_add_f32 v[80:81], v[80:81], v[144:145]
	s_and_b64 vcc, exec, s[10:11]
	global_store_dwordx4 v[212:213], v[80:83], off offset:576 nt
	s_cbranch_vccnz .LBB0_907
	v_or_b32_e32 v96, 0x120, v96
	v_cvt_pk_bf16_f32 v98, v80, v81
	v_cvt_pk_bf16_f32 v99, v82, v83
	v_lshl_add_u64 v[96:97], s[40:41], 0, v[96:97]
	global_store_dwordx2 v[96:97], v[98:99], off

; __device__ __forceinline__ unsigned cvt_pk_bf16(float lo, float hi) { f32x2 v = {lo, hi}; bf16x2_t b = __builtin_convertvector(v, bf16x2_t); return __builtin_bit_cast(unsigned, b); }
;     __device__ __forceinline__ void operator()(const f32x4 (&acc)[2][2][4][2], const Unit& u, int wr, int wc, int fr, int fq) const {
;     ...
;             for (int m = 0; m < 4; ++m) { const int row = row0 + ai * HALF + m * 16; const size_t off = (size_t)row * DMODEL + col0; float sq = 0.f;
; #pragma unroll
;                 for (int bj = 0; bj < 2; ++bj)
; #pragma unroll
;                     for (int n = 0; n < 2; ++n) { const size_t o2 = off + bj * HALF + n * 16; const f32x4 o = bs[m][bj][n] + acc[ai][bj][m][n] * alpha;
;                         *(f32x4*)(out + o2) = o; sq += (o[0] * o[0] + o[1] * o[1]) + (o[2] * o[2] + o[3] * o[3]);
;                         if (outb) { u32x2 w; w.x = cvt_pk_bf16(o[0], o[1]); w.y = cvt_pk_bf16(o[2], o[3]); *(u32x2*)(outb + o2) = w; } }
.LBB0_909:
	s_or_b64 exec, exec, s[12:13]
	s_waitcnt lgkmcnt(0)
	v_lshlrev_b64 v[80:81], 11, v[206:207]
	v_lshl_add_u64 v[80:81], v[80:81], 0, v[200:201]
	v_pk_add_f32 v[78:79], v[78:79], v[142:143]
	v_pk_add_f32 v[76:77], v[76:77], v[140:141]
	s_and_b64 vcc, exec, s[10:11]
	global_store_dwordx4 v[208:209], v[76:79], off nt
	s_cbranch_vccnz .LBB0_911
	v_cvt_pk_bf16_f32 v82, v76, v77
	v_cvt_pk_bf16_f32 v83, v78, v79
	v_lshl_add_u64 v[84:85], v[80:81], 1, s[40:41]
	global_store_dwordx2 v[84:85], v[82:83], off
.LBB0_911:
	v_pk_add_f32 v[74:75], v[74:75], v[138:139]
	v_pk_add_f32 v[72:73], v[72:73], v[136:137]
	s_and_b64 vcc, exec, s[10:11]
	v_lshlrev_b64 v[80:81], 1, v[80:81]
	global_store_dwordx4 v[208:209], v[72:75], off offset:64 nt
	s_cbranch_vccnz .LBB0_913
	v_or_b32_e32 v84, 32, v80
	v_mov_b32_e32 v85, v81
	v_cvt_pk_bf16_f32 v82, v72, v73
	v_cvt_pk_bf16_f32 v83, v74, v75
	v_lshl_add_u64 v[84:85], s[40:41], 0, v[84:85]
	global_store_dwordx2 v[84:85], v[82:83], off
.LBB0_913:
	v_pk_add_f32 v[70:71], v[70:71], v[134:135]
	v_pk_add_f32 v[68:69], v[68:69], v[132:133]
	s_and_b64 vcc, exec, s[10:11]
	global_store_dwordx4 v[208:209], v[68:71], off offset:512 nt
	s_cbranch_vccnz .LBB0_915
	v_or_b32_e32 v84, 0x100, v80
	v_mov_b32_e32 v85, v81
	v_cvt_pk_bf16_f32 v82, v68, v69
	v_cvt_pk_bf16_f32 v83, v70, v71
	v_lshl_add_u64 v[84:85], s[40:41], 0, v[84:85]
	global_store_dwordx2 v[84:85], v[82:83], off
.LBB0_915:
	v_pk_add_f32 v[66:67], v[66:67], v[130:131]
	v_pk_add_f32 v[64:65], v[64:65], v[128:129]
	s_and_b64 vcc, exec, s[10:11]
	global_store_dwordx4 v[208:209], v[64:67], off offset:576 nt
	s_cbranch_vccnz .LBB0_917
	v_or_b32_e32 v80, 0x120, v80
	v_cvt_pk_bf16_f32 v82, v64, v65
	v_cvt_pk_bf16_f32 v83, v66, v67
	v_lshl_add_u64 v[80:81], s[40:41], 0, v[80:81]
	global_store_dwordx2 v[80:81], v[82:83], off

; __device__ __forceinline__ unsigned cvt_pk_bf16(float lo, float hi) { f32x2 v = {lo, hi}; bf16x2_t b = __builtin_convertvector(v, bf16x2_t); return __builtin_bit_cast(unsigned, b); }
;     __device__ __forceinline__ void operator()(const f32x4 (&acc)[2][2][4][2], const Unit& u, int wr, int wc, int fr, int fq) const {
;     ...
;                     for (int n = 0; n < 2; ++n) bs[m][bj][n] = *(const f32x4*)(base + (size_t)(row0 + ai * HALF + m * 16) * DMODEL + col0 + bj * HALF + n * 16);
; #pragma unroll
;             for (int m = 0; m < 4; ++m) { const int row = row0 + ai * HALF + m * 16; const size_t off = (size_t)row * DMODEL + col0; float sq = 0.f;
; #pragma unroll
;                 for (int bj = 0; bj < 2; ++bj)
; #pragma unroll
;                     for (int n = 0; n < 2; ++n) { const size_t o2 = off + bj * HALF + n * 16; const f32x4 o = bs[m][bj][n] + acc[ai][bj][m][n] * alpha;
;                         *(f32x4*)(out + o2) = o; sq += (o[0] * o[0] + o[1] * o[1]) + (o[2] * o[2] + o[3] * o[3]);
;                         if (outb) { u32x2 w; w.x = cvt_pk_bf16(o[0], o[1]); w.y = cvt_pk_bf16(o[2], o[3]); *(u32x2*)(outb + o2) = w; } }
.LBB0_919:
	s_or_b64 exec, exec, s[12:13]
	v_add_u32_e32 v136, 0x80, v204
	v_ashrrev_i32_e32 v137, 31, v136
	v_add_u32_e32 v132, 0x90, v204
	s_waitcnt lgkmcnt(0)
	v_lshlrev_b64 v[64:65], 13, v[136:137]
	v_ashrrev_i32_e32 v133, 31, v132
	v_add_u32_e32 v128, 0xa0, v204
	v_lshl_add_u64 v[138:139], v[202:203], 0, v[64:65]
	v_lshlrev_b64 v[64:65], 13, v[132:133]
	v_ashrrev_i32_e32 v129, 31, v128
	v_add_u32_e32 v124, 0xb0, v204
	v_lshl_add_u64 v[134:135], v[202:203], 0, v[64:65]
	v_lshlrev_b64 v[64:65], 13, v[128:129]
	v_ashrrev_i32_e32 v125, 31, v124
	v_lshl_add_u64 v[130:131], v[202:203], 0, v[64:65]
	v_lshlrev_b64 v[64:65], 13, v[124:125]
	v_lshl_add_u64 v[126:127], v[202:203], 0, v[64:65]
	global_load_dwordx4 v[142:145], v[138:139], off nt
	global_load_dwordx4 v[120:123], v[138:139], off offset:64 nt
	global_load_dwordx4 v[116:119], v[138:139], off offset:512 nt
	global_load_dwordx4 v[112:115], v[138:139], off offset:576 nt
	global_load_dwordx4 v[108:111], v[134:135], off nt
	global_load_dwordx4 v[104:107], v[134:135], off offset:64 nt
	global_load_dwordx4 v[100:103], v[134:135], off offset:512 nt
	global_load_dwordx4 v[96:99], v[134:135], off offset:576 nt
	global_load_dwordx4 v[92:95], v[130:131], off nt
	global_load_dwordx4 v[88:91], v[130:131], off offset:64 nt
	global_load_dwordx4 v[84:87], v[130:131], off offset:512 nt
	global_load_dwordx4 v[80:83], v[130:131], off offset:576 nt
	global_load_dwordx4 v[76:79], v[126:127], off nt
	global_load_dwordx4 v[72:75], v[126:127], off offset:64 nt
	global_load_dwordx4 v[68:71], v[126:127], off offset:512 nt
	global_load_dwordx4 v[64:67], v[126:127], off offset:576 nt
	v_lshlrev_b64 v[140:141], 11, v[136:137]
	v_lshl_add_u64 v[140:141], v[140:141], 0, v[200:201]
	s_and_b64 vcc, exec, s[10:11]
	s_waitcnt vmcnt(15)
	v_pk_add_f32 v[62:63], v[62:63], v[144:145]
	v_pk_add_f32 v[60:61], v[60:61], v[142:143]
	global_store_dwordx4 v[138:139], v[60:63], off nt
	s_cbranch_vccnz .LBB0_921
	v_cvt_pk_bf16_f32 v142, v60, v61
	v_cvt_pk_bf16_f32 v143, v62, v63
	v_lshl_add_u64 v[144:145], v[140:141], 1, s[40:41]
	global_store_dwordx2 v[144:145], v[142:143], off
.LBB0_921:
	s_waitcnt vmcnt(15)
	v_pk_add_f32 v[58:59], v[58:59], v[122:123]
	v_pk_add_f32 v[56:57], v[56:57], v[120:121]
	s_and_b64 vcc, exec, s[10:11]
	v_lshlrev_b64 v[120:121], 1, v[140:141]
	global_store_dwordx4 v[138:139], v[56:59], off offset:64 nt
	s_cbranch_vccnz .LBB0_923
	v_or_b32_e32 v140, 32, v120
	v_mov_b32_e32 v141, v121
	v_cvt_pk_bf16_f32 v122, v56, v57
	v_cvt_pk_bf16_f32 v123, v58, v59
	v_lshl_add_u64 v[140:141], s[40:41], 0, v[140:141]
	global_store_dwordx2 v[140:141], v[122:123], off
.LBB0_923:
	s_waitcnt vmcnt(15)
	v_pk_add_f32 v[54:55], v[54:55], v[118:119]
	v_pk_add_f32 v[52:53], v[52:53], v[116:117]
	s_and_b64 vcc, exec, s[10:11]
	global_store_dwordx4 v[138:139], v[52:55], off offset:512 nt
	s_cbranch_vccnz .LBB0_925
	v_or_b32_e32 v118, 0x100, v120
	v_mov_b32_e32 v119, v121
	v_cvt_pk_bf16_f32 v116, v52, v53
	v_cvt_pk_bf16_f32 v117, v54, v55
	v_lshl_add_u64 v[118:119], s[40:41], 0, v[118:119]
	global_store_dwordx2 v[118:119], v[116:117], off
.LBB0_925:
	s_waitcnt vmcnt(15)
	v_pk_add_f32 v[50:51], v[50:51], v[114:115]
	v_pk_add_f32 v[48:49], v[48:49], v[112:113]
	s_and_b64 vcc, exec, s[10:11]
	global_store_dwordx4 v[138:139], v[48:51], off offset:576 nt
	s_cbranch_vccnz .LBB0_927
	v_or_b32_e32 v120, 0x120, v120
	v_cvt_pk_bf16_f32 v112, v48, v49
	v_cvt_pk_bf16_f32 v113, v50, v51
	v_lshl_add_u64 v[114:115], s[40:41], 0, v[120:121]
	global_store_dwordx2 v[114:115], v[112:113], off

; __device__ __forceinline__ unsigned cvt_pk_bf16(float lo, float hi) { f32x2 v = {lo, hi}; bf16x2_t b = __builtin_convertvector(v, bf16x2_t); return __builtin_bit_cast(unsigned, b); }
;     __device__ __forceinline__ void operator()(const f32x4 (&acc)[2][2][4][2], const Unit& u, int wr, int wc, int fr, int fq) const {
;     ...
;             for (int m = 0; m < 4; ++m) { const int row = row0 + ai * HALF + m * 16; const size_t off = (size_t)row * DMODEL + col0; float sq = 0.f;
; #pragma unroll
;                 for (int bj = 0; bj < 2; ++bj)
; #pragma unroll
;                     for (int n = 0; n < 2; ++n) { const size_t o2 = off + bj * HALF + n * 16; const f32x4 o = bs[m][bj][n] + acc[ai][bj][m][n] * alpha;
;                         *(f32x4*)(out + o2) = o; sq += (o[0] * o[0] + o[1] * o[1]) + (o[2] * o[2] + o[3] * o[3]);
;                         if (outb) { u32x2 w; w.x = cvt_pk_bf16(o[0], o[1]); w.y = cvt_pk_bf16(o[2], o[3]); *(u32x2*)(outb + o2) = w; } }
.LBB0_929:
	s_or_b64 exec, exec, s[12:13]
	s_waitcnt lgkmcnt(0)
	v_lshlrev_b64 v[48:49], 11, v[132:133]
	v_lshl_add_u64 v[48:49], v[48:49], 0, v[200:201]
	s_waitcnt vmcnt(15)
	v_pk_add_f32 v[46:47], v[46:47], v[110:111]
	v_pk_add_f32 v[44:45], v[44:45], v[108:109]
	s_and_b64 vcc, exec, s[10:11]
	global_store_dwordx4 v[134:135], v[44:47], off nt
	s_cbranch_vccnz .LBB0_931
	v_cvt_pk_bf16_f32 v50, v44, v45
	v_cvt_pk_bf16_f32 v51, v46, v47
	v_lshl_add_u64 v[52:53], v[48:49], 1, s[40:41]
	global_store_dwordx2 v[52:53], v[50:51], off
.LBB0_931:
	s_waitcnt vmcnt(15)
	v_pk_add_f32 v[42:43], v[42:43], v[106:107]
	v_pk_add_f32 v[40:41], v[40:41], v[104:105]
	s_and_b64 vcc, exec, s[10:11]
	v_lshlrev_b64 v[48:49], 1, v[48:49]
	global_store_dwordx4 v[134:135], v[40:43], off offset:64 nt
	s_cbranch_vccnz .LBB0_933
	v_or_b32_e32 v52, 32, v48
	v_mov_b32_e32 v53, v49
	v_cvt_pk_bf16_f32 v50, v40, v41
	v_cvt_pk_bf16_f32 v51, v42, v43
	v_lshl_add_u64 v[52:53], s[40:41], 0, v[52:53]
	global_store_dwordx2 v[52:53], v[50:51], off
.LBB0_933:
	s_waitcnt vmcnt(15)
	v_pk_add_f32 v[38:39], v[38:39], v[102:103]
	v_pk_add_f32 v[36:37], v[36:37], v[100:101]
	s_and_b64 vcc, exec, s[10:11]
	global_store_dwordx4 v[134:135], v[36:39], off offset:512 nt
	s_cbranch_vccnz .LBB0_935
	v_or_b32_e32 v52, 0x100, v48
	v_mov_b32_e32 v53, v49
	v_cvt_pk_bf16_f32 v50, v36, v37
	v_cvt_pk_bf16_f32 v51, v38, v39
	v_lshl_add_u64 v[52:53], s[40:41], 0, v[52:53]
	global_store_dwordx2 v[52:53], v[50:51], off
.LBB0_935:
	s_waitcnt vmcnt(15)
	v_pk_add_f32 v[34:35], v[34:35], v[98:99]
	v_pk_add_f32 v[32:33], v[32:33], v[96:97]
	s_and_b64 vcc, exec, s[10:11]
	global_store_dwordx4 v[134:135], v[32:35], off offset:576 nt
	s_cbranch_vccnz .LBB0_937
	v_or_b32_e32 v48, 0x120, v48
	v_cvt_pk_bf16_f32 v50, v32, v33
	v_cvt_pk_bf16_f32 v51, v34, v35
	v_lshl_add_u64 v[48:49], s[40:41], 0, v[48:49]
	global_store_dwordx2 v[48:49], v[50:51], off

; __device__ __forceinline__ unsigned cvt_pk_bf16(float lo, float hi) { f32x2 v = {lo, hi}; bf16x2_t b = __builtin_convertvector(v, bf16x2_t); return __builtin_bit_cast(unsigned, b); }
;     __device__ __forceinline__ void operator()(const f32x4 (&acc)[2][2][4][2], const Unit& u, int wr, int wc, int fr, int fq) const {
;     ...
;             for (int m = 0; m < 4; ++m) { const int row = row0 + ai * HALF + m * 16; const size_t off = (size_t)row * DMODEL + col0; float sq = 0.f;
; #pragma unroll
;                 for (int bj = 0; bj < 2; ++bj)
; #pragma unroll
;                     for (int n = 0; n < 2; ++n) { const size_t o2 = off + bj * HALF + n * 16; const f32x4 o = bs[m][bj][n] + acc[ai][bj][m][n] * alpha;
;                         *(f32x4*)(out + o2) = o; sq += (o[0] * o[0] + o[1] * o[1]) + (o[2] * o[2] + o[3] * o[3]);
;                         if (outb) { u32x2 w; w.x = cvt_pk_bf16(o[0], o[1]); w.y = cvt_pk_bf16(o[2], o[3]); *(u32x2*)(outb + o2) = w; } }
.LBB0_939:
	s_or_b64 exec, exec, s[12:13]
	s_waitcnt lgkmcnt(0)
	v_lshlrev_b64 v[32:33], 11, v[128:129]
	v_lshl_add_u64 v[32:33], v[32:33], 0, v[200:201]
	s_waitcnt vmcnt(15)
	v_pk_add_f32 v[30:31], v[30:31], v[94:95]
	v_pk_add_f32 v[28:29], v[28:29], v[92:93]
	s_and_b64 vcc, exec, s[10:11]
	global_store_dwordx4 v[130:131], v[28:31], off nt
	s_cbranch_vccnz .LBB0_941
	v_cvt_pk_bf16_f32 v34, v28, v29
	v_cvt_pk_bf16_f32 v35, v30, v31
	v_lshl_add_u64 v[36:37], v[32:33], 1, s[40:41]
	global_store_dwordx2 v[36:37], v[34:35], off
.LBB0_941:
	s_waitcnt vmcnt(15)
	v_pk_add_f32 v[26:27], v[26:27], v[90:91]
	v_pk_add_f32 v[24:25], v[24:25], v[88:89]
	s_and_b64 vcc, exec, s[10:11]
	v_lshlrev_b64 v[32:33], 1, v[32:33]
	global_store_dwordx4 v[130:131], v[24:27], off offset:64 nt
	s_cbranch_vccnz .LBB0_943
	v_or_b32_e32 v36, 32, v32
	v_mov_b32_e32 v37, v33
	v_cvt_pk_bf16_f32 v34, v24, v25
	v_cvt_pk_bf16_f32 v35, v26, v27
	v_lshl_add_u64 v[36:37], s[40:41], 0, v[36:37]
	global_store_dwordx2 v[36:37], v[34:35], off
.LBB0_943:
	s_waitcnt vmcnt(15)
	v_pk_add_f32 v[22:23], v[22:23], v[86:87]
	v_pk_add_f32 v[20:21], v[20:21], v[84:85]
	s_and_b64 vcc, exec, s[10:11]
	global_store_dwordx4 v[130:131], v[20:23], off offset:512 nt
	s_cbranch_vccnz .LBB0_945
	v_or_b32_e32 v36, 0x100, v32
	v_mov_b32_e32 v37, v33
	v_cvt_pk_bf16_f32 v34, v20, v21
	v_cvt_pk_bf16_f32 v35, v22, v23
	v_lshl_add_u64 v[36:37], s[40:41], 0, v[36:37]
	global_store_dwordx2 v[36:37], v[34:35], off
.LBB0_945:
	s_waitcnt vmcnt(15)
	v_pk_add_f32 v[18:19], v[18:19], v[82:83]
	v_pk_add_f32 v[16:17], v[16:17], v[80:81]
	s_and_b64 vcc, exec, s[10:11]
	global_store_dwordx4 v[130:131], v[16:19], off offset:576 nt
	s_cbranch_vccnz .LBB0_947
	v_or_b32_e32 v32, 0x120, v32
	v_cvt_pk_bf16_f32 v34, v16, v17
	v_cvt_pk_bf16_f32 v35, v18, v19
	v_lshl_add_u64 v[32:33], s[40:41], 0, v[32:33]
	global_store_dwordx2 v[32:33], v[34:35], off

; __device__ __forceinline__ unsigned cvt_pk_bf16(float lo, float hi) { f32x2 v = {lo, hi}; bf16x2_t b = __builtin_convertvector(v, bf16x2_t); return __builtin_bit_cast(unsigned, b); }
;     __device__ __forceinline__ void operator()(const f32x4 (&acc)[2][2][4][2], const Unit& u, int wr, int wc, int fr, int fq) const {
;     ...
;             for (int m = 0; m < 4; ++m) { const int row = row0 + ai * HALF + m * 16; const size_t off = (size_t)row * DMODEL + col0; float sq = 0.f;
; #pragma unroll
;                 for (int bj = 0; bj < 2; ++bj)
; #pragma unroll
;                     for (int n = 0; n < 2; ++n) { const size_t o2 = off + bj * HALF + n * 16; const f32x4 o = bs[m][bj][n] + acc[ai][bj][m][n] * alpha;
;                         *(f32x4*)(out + o2) = o; sq += (o[0] * o[0] + o[1] * o[1]) + (o[2] * o[2] + o[3] * o[3]);
;                         if (outb) { u32x2 w; w.x = cvt_pk_bf16(o[0], o[1]); w.y = cvt_pk_bf16(o[2], o[3]); *(u32x2*)(outb + o2) = w; } }
.LBB0_949:
	s_or_b64 exec, exec, s[12:13]
	s_waitcnt lgkmcnt(0)
	v_lshlrev_b64 v[16:17], 11, v[124:125]
	v_lshl_add_u64 v[16:17], v[16:17], 0, v[200:201]
	s_waitcnt vmcnt(15)
	v_pk_add_f32 v[14:15], v[14:15], v[78:79]
	v_pk_add_f32 v[12:13], v[12:13], v[76:77]
	s_and_b64 vcc, exec, s[10:11]
	global_store_dwordx4 v[126:127], v[12:15], off nt
	s_cbranch_vccnz .LBB0_951
	v_cvt_pk_bf16_f32 v18, v12, v13
	v_cvt_pk_bf16_f32 v19, v14, v15
	v_lshl_add_u64 v[20:21], v[16:17], 1, s[40:41]
	global_store_dwordx2 v[20:21], v[18:19], off
.LBB0_951:
	s_waitcnt vmcnt(15)
	v_pk_add_f32 v[10:11], v[10:11], v[74:75]
	v_pk_add_f32 v[8:9], v[8:9], v[72:73]
	s_and_b64 vcc, exec, s[10:11]
	v_lshlrev_b64 v[16:17], 1, v[16:17]
	global_store_dwordx4 v[126:127], v[8:11], off offset:64 nt
	s_cbranch_vccnz .LBB0_953
	v_or_b32_e32 v20, 32, v16
	v_mov_b32_e32 v21, v17
	v_cvt_pk_bf16_f32 v18, v8, v9
	v_cvt_pk_bf16_f32 v19, v10, v11
	v_lshl_add_u64 v[20:21], s[40:41], 0, v[20:21]
	global_store_dwordx2 v[20:21], v[18:19], off
.LBB0_953:
	s_waitcnt vmcnt(15)
	v_pk_add_f32 v[6:7], v[6:7], v[70:71]
	v_pk_add_f32 v[4:5], v[4:5], v[68:69]
	s_and_b64 vcc, exec, s[10:11]
	global_store_dwordx4 v[126:127], v[4:7], off offset:512 nt
	s_cbranch_vccnz .LBB0_955
	v_or_b32_e32 v20, 0x100, v16
	v_mov_b32_e32 v21, v17
	v_cvt_pk_bf16_f32 v18, v4, v5
	v_cvt_pk_bf16_f32 v19, v6, v7
	v_lshl_add_u64 v[20:21], s[40:41], 0, v[20:21]
	global_store_dwordx2 v[20:21], v[18:19], off
.LBB0_955:
	s_waitcnt vmcnt(15)
	v_pk_add_f32 v[2:3], v[2:3], v[66:67]
	v_pk_add_f32 v[0:1], v[0:1], v[64:65]
	s_and_b64 vcc, exec, s[10:11]
	global_store_dwordx4 v[126:127], v[0:3], off offset:576 nt
	s_cbranch_vccnz .LBB0_957
	v_or_b32_e32 v16, 0x120, v16
	v_cvt_pk_bf16_f32 v18, v0, v1
	v_cvt_pk_bf16_f32 v19, v2, v3
	v_lshl_add_u64 v[16:17], s[40:41], 0, v[16:17]
	global_store_dwordx2 v[16:17], v[18:19], off

; __device__ __forceinline__ unsigned cvt_pk_bf16(float lo, float hi) { f32x2 v = {lo, hi}; bf16x2_t b = __builtin_convertvector(v, bf16x2_t); return __builtin_bit_cast(unsigned, b); }
;     __device__ __forceinline__ void operator()(const f32x4 (&acc)[2][2][4][2], const Unit& u, int wr, int wc, int fr, int fq) const {
;     ...
;                     for (int n = 0; n < 2; ++n) bs[m][bj][n] = *(const f32x4*)(base + (size_t)(row0 + ai * HALF + m * 16) * DMODEL + col0 + bj * HALF + n * 16);
; #pragma unroll
;             for (int m = 0; m < 4; ++m) { const int row = row0 + ai * HALF + m * 16; const size_t off = (size_t)row * DMODEL + col0; float sq = 0.f;
; #pragma unroll
;                 for (int bj = 0; bj < 2; ++bj)
; #pragma unroll
;                     for (int n = 0; n < 2; ++n) { const size_t o2 = off + bj * HALF + n * 16; const f32x4 o = bs[m][bj][n] + acc[ai][bj][m][n] * alpha;
;                         *(f32x4*)(out + o2) = o; sq += (o[0] * o[0] + o[1] * o[1]) + (o[2] * o[2] + o[3] * o[3]);
;                         if (outb) { u32x2 w; w.x = cvt_pk_bf16(o[0], o[1]); w.y = cvt_pk_bf16(o[2], o[3]); *(u32x2*)(outb + o2) = w; } }
;                 sq += __shfl_xor(sq, 16); sq += __shfl_xor(sq, 32);
;                 if (fq == 0) ssq_out[(size_t)row * 32 + u.pn * 4 + wc] = sq; }
.LBB0_1111:
	v_lshl_or_b32 v188, s0, 8, v208
	v_lshl_add_u32 v192, s12, 8, v206
	v_ashrrev_i32_e32 v189, 31, v188
	v_lshlrev_b64 v[220:221], 2, v[188:189]
	v_ashrrev_i32_e32 v193, 31, v192
	v_lshl_add_u64 v[190:191], s[56:57], 0, v[220:221]
	v_lshlrev_b64 v[234:235], 13, v[192:193]
	v_lshl_add_u64 v[128:129], v[190:191], 0, v[234:235]
	global_load_dwordx4 v[212:215], v[128:129], off nt
	global_load_dwordx4 v[216:219], v[128:129], off offset:64 nt
	global_load_dwordx4 v[226:229], v[128:129], off offset:512 nt
	global_load_dwordx4 v[230:233], v[128:129], off offset:576 nt
	v_or_b32_e32 v202, 16, v192
	v_or_b32_e32 v198, 32, v192
	v_or_b32_e32 v194, 48, v192
	v_ashrrev_i32_e32 v203, 31, v202
	v_ashrrev_i32_e32 v199, 31, v198
	v_ashrrev_i32_e32 v195, 31, v194
	v_lshlrev_b64 v[204:205], 13, v[202:203]
	v_lshlrev_b64 v[200:201], 13, v[198:199]
	v_lshlrev_b64 v[196:197], 13, v[194:195]
	v_lshl_add_u64 v[128:129], v[190:191], 0, v[204:205]
	v_lshl_add_u64 v[130:131], v[190:191], 0, v[200:201]
	v_lshl_add_u64 v[236:237], v[190:191], 0, v[196:197]
	global_load_dwordx4 v[172:175], v[128:129], off nt
	global_load_dwordx4 v[168:171], v[128:129], off offset:64 nt
	global_load_dwordx4 v[164:167], v[128:129], off offset:512 nt
	global_load_dwordx4 v[160:163], v[128:129], off offset:576 nt
	global_load_dwordx4 v[156:159], v[130:131], off nt
	global_load_dwordx4 v[152:155], v[130:131], off offset:64 nt
	global_load_dwordx4 v[148:151], v[130:131], off offset:512 nt
	global_load_dwordx4 v[144:147], v[130:131], off offset:576 nt
	global_load_dwordx4 v[140:143], v[236:237], off nt
	global_load_dwordx4 v[136:139], v[236:237], off offset:64 nt
	global_load_dwordx4 v[132:135], v[236:237], off offset:512 nt
	s_nop 0
	global_load_dwordx4 v[128:131], v[236:237], off offset:576 nt
	s_lshl_b32 s28, s0, 2
	s_ashr_i32 s29, s28, 31
	s_waitcnt vmcnt(0)
	v_pk_fma_f32 v[126:127], v[126:127], 0.5, v[214:215] op_sel_hi:[1,0,1]
	v_pk_fma_f32 v[124:125], v[124:125], 0.5, v[212:213] op_sel_hi:[1,0,1]
	v_pk_fma_f32 v[122:123], v[122:123], 0.5, v[218:219] op_sel_hi:[1,0,1]
	v_pk_fma_f32 v[120:121], v[120:121], 0.5, v[216:217] op_sel_hi:[1,0,1]
	v_pk_fma_f32 v[118:119], v[118:119], 0.5, v[228:229] op_sel_hi:[1,0,1]
	v_pk_fma_f32 v[116:117], v[116:117], 0.5, v[226:227] op_sel_hi:[1,0,1]
	v_pk_fma_f32 v[214:215], v[114:115], 0.5, v[232:233] op_sel_hi:[1,0,1]
	v_pk_fma_f32 v[212:213], v[112:113], 0.5, v[230:231] op_sel_hi:[1,0,1]
	v_mul_f32_e32 v112, v125, v125
	v_mul_f32_e32 v113, v127, v127
	v_mul_f32_e32 v114, v121, v121
	v_mul_f32_e32 v115, v123, v123
	v_mul_f32_e32 v216, v117, v117
	v_mul_f32_e32 v217, v119, v119
	v_fmac_f32_e32 v112, v124, v124
	v_fmac_f32_e32 v113, v126, v126
	v_fmac_f32_e32 v114, v120, v120
	v_fmac_f32_e32 v115, v122, v122
	v_mul_f32_e32 v218, v213, v213
	v_mul_f32_e32 v219, v215, v215
	v_fmac_f32_e32 v216, v116, v116
	v_fmac_f32_e32 v217, v118, v118
	v_add_f32_e32 v112, v112, v113
	v_add_f32_e32 v113, v114, v115
	v_fmac_f32_e32 v218, v212, v212
	v_fmac_f32_e32 v219, v214, v214
	v_add_f32_e32 v114, v216, v217
	v_add_f32_e32 v112, v112, v113
	v_add_f32_e32 v112, v112, v114
	v_add_f32_e32 v113, v218, v219
	v_add_f32_e32 v216, v112, v113
	ds_bpermute_b32 v217, v224, v216
	v_lshl_add_u64 v[112:113], s[56:57], 0, v[234:235]
	v_lshl_add_u64 v[114:115], v[112:113], 0, v[220:221]
	global_store_dwordx4 v[114:115], v[124:127], off
	global_store_dwordx4 v[114:115], v[120:123], off offset:64
	global_store_dwordx4 v[114:115], v[116:119], off offset:512
	global_store_dwordx4 v[114:115], v[212:215], off offset:576
	s_waitcnt lgkmcnt(0)
	v_add_f32_e32 v112, v216, v217
	ds_bpermute_b32 v113, v223, v112
	s_and_saveexec_b64 s[12:13], s[6:7]
	s_cbranch_execz .LBB0_1113
	v_lshlrev_b64 v[114:115], 7, v[192:193]
	v_lshl_add_u64 v[114:115], s[18:19], 0, v[114:115]
	v_lshl_add_u64 v[114:115], s[28:29], 2, v[114:115]
	s_lshl_b32 s0, s35, 2
	v_lshl_add_u64 v[114:115], v[114:115], 0, s[0:1]
	s_waitcnt lgkmcnt(0)
	v_add_f32_e32 v112, v112, v113
	global_store_dword v[114:115], v112, off

; __device__ __forceinline__ unsigned cvt_pk_bf16(float lo, float hi) { f32x2 v = {lo, hi}; bf16x2_t b = __builtin_convertvector(v, bf16x2_t); return __builtin_bit_cast(unsigned, b); }
;     __device__ __forceinline__ void operator()(const f32x4 (&acc)[2][2][4][2], const Unit& u, int wr, int wc, int fr, int fq) const {
;     ...
;                     for (int n = 0; n < 2; ++n) bs[m][bj][n] = *(const f32x4*)(base + (size_t)(row0 + ai * HALF + m * 16) * DMODEL + col0 + bj * HALF + n * 16);
; #pragma unroll
;             for (int m = 0; m < 4; ++m) { const int row = row0 + ai * HALF + m * 16; const size_t off = (size_t)row * DMODEL + col0; float sq = 0.f;
; #pragma unroll
;                 for (int bj = 0; bj < 2; ++bj)
; #pragma unroll
;                     for (int n = 0; n < 2; ++n) { const size_t o2 = off + bj * HALF + n * 16; const f32x4 o = bs[m][bj][n] + acc[ai][bj][m][n] * alpha;
;                         *(f32x4*)(out + o2) = o; sq += (o[0] * o[0] + o[1] * o[1]) + (o[2] * o[2] + o[3] * o[3]);
;                         if (outb) { u32x2 w; w.x = cvt_pk_bf16(o[0], o[1]); w.y = cvt_pk_bf16(o[2], o[3]); *(u32x2*)(outb + o2) = w; } }
;                 sq += __shfl_xor(sq, 16); sq += __shfl_xor(sq, 32);
;                 if (fq == 0) ssq_out[(size_t)row * 32 + u.pn * 4 + wc] = sq; }
.LBB0_1119:
	s_or_b64 exec, exec, s[12:13]
	v_add_u32_e32 v124, 0x80, v192
	v_ashrrev_i32_e32 v125, 31, v124
	v_lshlrev_b64 v[142:143], 13, v[124:125]
	s_waitcnt lgkmcnt(0)
	v_lshl_add_u64 v[64:65], v[190:191], 0, v[142:143]
	global_load_dwordx4 v[126:129], v[64:65], off nt
	global_load_dwordx4 v[130:133], v[64:65], off offset:64 nt
	global_load_dwordx4 v[134:137], v[64:65], off offset:512 nt
	global_load_dwordx4 v[138:141], v[64:65], off offset:576 nt
	v_add_u32_e32 v120, 0x90, v192
	v_add_u32_e32 v116, 0xa0, v192
	v_add_u32_e32 v112, 0xb0, v192
	v_ashrrev_i32_e32 v121, 31, v120
	v_ashrrev_i32_e32 v117, 31, v116
	v_ashrrev_i32_e32 v113, 31, v112
	v_lshlrev_b64 v[122:123], 13, v[120:121]
	v_lshlrev_b64 v[118:119], 13, v[116:117]
	v_lshlrev_b64 v[114:115], 13, v[112:113]
	v_lshl_add_u64 v[64:65], v[190:191], 0, v[122:123]
	v_lshl_add_u64 v[66:67], v[190:191], 0, v[118:119]
	v_lshl_add_u64 v[144:145], v[190:191], 0, v[114:115]
	global_load_dwordx4 v[108:111], v[64:65], off nt
	global_load_dwordx4 v[104:107], v[64:65], off offset:64 nt
	global_load_dwordx4 v[100:103], v[64:65], off offset:512 nt
	global_load_dwordx4 v[96:99], v[64:65], off offset:576 nt
	global_load_dwordx4 v[92:95], v[66:67], off nt
	global_load_dwordx4 v[88:91], v[66:67], off offset:64 nt
	global_load_dwordx4 v[84:87], v[66:67], off offset:512 nt
	global_load_dwordx4 v[80:83], v[66:67], off offset:576 nt
	global_load_dwordx4 v[76:79], v[144:145], off nt
	global_load_dwordx4 v[72:75], v[144:145], off offset:64 nt
	global_load_dwordx4 v[68:71], v[144:145], off offset:512 nt
	s_nop 0
	global_load_dwordx4 v[64:67], v[144:145], off offset:576 nt
	s_waitcnt vmcnt(15)
	v_pk_fma_f32 v[62:63], v[62:63], 0.5, v[128:129] op_sel_hi:[1,0,1]
	v_pk_fma_f32 v[60:61], v[60:61], 0.5, v[126:127] op_sel_hi:[1,0,1]
	s_waitcnt vmcnt(14)
	v_pk_fma_f32 v[58:59], v[58:59], 0.5, v[132:133] op_sel_hi:[1,0,1]
	v_pk_fma_f32 v[56:57], v[56:57], 0.5, v[130:131] op_sel_hi:[1,0,1]
	s_waitcnt vmcnt(13)
	v_pk_fma_f32 v[54:55], v[54:55], 0.5, v[136:137] op_sel_hi:[1,0,1]
	v_pk_fma_f32 v[52:53], v[52:53], 0.5, v[134:135] op_sel_hi:[1,0,1]
	s_waitcnt vmcnt(12)
	v_pk_fma_f32 v[128:129], v[50:51], 0.5, v[140:141] op_sel_hi:[1,0,1]
	v_pk_fma_f32 v[126:127], v[48:49], 0.5, v[138:139] op_sel_hi:[1,0,1]
	v_mul_f32_e32 v48, v61, v61
	v_mul_f32_e32 v49, v63, v63
	v_mul_f32_e32 v50, v57, v57
	v_mul_f32_e32 v51, v59, v59
	v_mul_f32_e32 v130, v53, v53
	v_mul_f32_e32 v131, v55, v55
	v_fmac_f32_e32 v48, v60, v60
	v_fmac_f32_e32 v49, v62, v62
	v_fmac_f32_e32 v50, v56, v56
	v_fmac_f32_e32 v51, v58, v58
	v_mul_f32_e32 v132, v127, v127
	v_mul_f32_e32 v133, v129, v129
	v_fmac_f32_e32 v130, v52, v52
	v_fmac_f32_e32 v131, v54, v54
	v_add_f32_e32 v48, v48, v49
	v_add_f32_e32 v49, v50, v51
	v_fmac_f32_e32 v132, v126, v126
	v_fmac_f32_e32 v133, v128, v128
	v_add_f32_e32 v50, v130, v131
	v_add_f32_e32 v48, v48, v49
	v_add_f32_e32 v48, v48, v50
	v_add_f32_e32 v49, v132, v133
	v_add_f32_e32 v130, v48, v49
	ds_bpermute_b32 v131, v224, v130
	v_lshl_add_u64 v[48:49], s[56:57], 0, v[142:143]
	v_lshl_add_u64 v[50:51], v[188:189], 2, v[48:49]
	global_store_dwordx4 v[50:51], v[60:63], off
	global_store_dwordx4 v[50:51], v[56:59], off offset:64
	global_store_dwordx4 v[50:51], v[52:55], off offset:512
	global_store_dwordx4 v[50:51], v[126:129], off offset:576
	s_waitcnt lgkmcnt(0)
	v_add_f32_e32 v48, v130, v131
	ds_bpermute_b32 v49, v223, v48
	s_and_saveexec_b64 s[12:13], s[6:7]
	s_cbranch_execz .LBB0_1121
	v_lshlrev_b64 v[50:51], 7, v[124:125]
	v_lshl_add_u64 v[50:51], s[18:19], 0, v[50:51]
	v_lshl_add_u64 v[50:51], s[28:29], 2, v[50:51]
	s_lshl_b32 s0, s35, 2
	v_lshl_add_u64 v[50:51], v[50:51], 0, s[0:1]
	s_waitcnt lgkmcnt(0)
	v_add_f32_e32 v48, v48, v49
	global_store_dword v[50:51], v48, off

; __device__ __forceinline__ float row_rstd(const float* ssq, int row) {
;     const f32x4* p = (const f32x4*)(ssq + (size_t)row * 32);
;     float s = 0.f;
; #pragma unroll
;     for (int i = 0; i < 8; ++i) { const f32x4 v = p[i]; s += (v[0] + v[1]) + (v[2] + v[3]); }
;     return __builtin_amdgcn_rsqf(s * (1.0f / DMODEL) + RMS_EPS);
; __global__ void __launch_bounds__(512, 2) mega_fwd(Args a) {
;     ...
;         for (int row = gw; row < M_TOK; row += NGW) {
;             const float rs = row_rstd(SSQ3, row);
;             f32x4* xr = (f32x4*)(XR + (size_t)row * DMODEL) + lane;
;             f32x4 xv[8];
; #pragma unroll
;             for (int j = 0; j < 8; ++j) xv[j] = xr[64 * j];
; #pragma unroll
;             for (int j = 0; j < 8; ++j) xr[64 * j] = xv[j] * rs * gf[64 * j];
.LBB0_1185:
	global_load_dwordx4 v[14:17], v1, s[8:9]
	global_load_dwordx4 v[18:21], v1, s[8:9] offset:16
	global_load_dwordx4 v[22:25], v1, s[8:9] offset:32
	global_load_dwordx4 v[26:29], v1, s[8:9] offset:48
	global_load_dwordx4 v[30:33], v1, s[8:9] offset:64
	global_load_dwordx4 v[34:37], v1, s[8:9] offset:80
	global_load_dwordx4 v[38:41], v1, s[8:9] offset:96
	global_load_dwordx4 v[42:45], v1, s[8:9] offset:112
	v_add_co_u32_e32 v58, vcc, s1, v12
	s_add_i32 s0, s0, s78
	s_nop 0
	v_addc_co_u32_e32 v59, vcc, -1, v13, vcc
	global_load_dwordx4 v[46:49], v[58:59], off offset:-3072
	global_load_dwordx4 v[50:53], v[2:3], off
	global_load_dwordx4 v[54:57], v[58:59], off offset:-2048
	s_add_u32 s8, s8, s10
	s_addc_u32 s9, s9, s11
	s_cmpk_lt_i32 s0, 0x2000
	s_waitcnt vmcnt(10)
	v_mov_b32_e32 v60, v14
	s_waitcnt vmcnt(9)
	v_mov_b32_e32 v61, v18
	v_mov_b32_e32 v18, v15
	v_mov_b32_e32 v14, v16
	v_mov_b32_e32 v15, v20
	v_mov_b32_e32 v20, v17
	s_waitcnt vmcnt(8)
	v_mov_b32_e32 v16, v23
	v_mov_b32_e32 v17, v24
	v_mov_b32_e32 v23, v25
	v_pk_add_f32 v[18:19], v[60:61], v[18:19]
	v_pk_add_f32 v[14:15], v[14:15], v[20:21]
	v_pk_add_f32 v[16:17], v[16:17], v[22:23]
	v_pk_add_f32 v[14:15], v[18:19], v[14:15]
	v_pk_add_f32 v[16:17], v[16:17], v[16:17] op_sel:[0,1] op_sel_hi:[1,0]
	v_add_f32_e32 v14, 0, v14
	s_waitcnt vmcnt(7)
	v_add_f32_e32 v24, v26, v27
	v_add_f32_e32 v26, v28, v29
	s_waitcnt vmcnt(6)
	v_mov_b32_e32 v29, v30
	v_mov_b32_e32 v25, v32
	v_mov_b32_e32 v27, v33
	v_mov_b32_e32 v17, v31
	v_add_f32_e32 v28, v14, v15
	s_waitcnt vmcnt(5)
	v_mov_b32_e32 v32, v35
	v_mov_b32_e32 v33, v36
	v_mov_b32_e32 v35, v37
	v_pk_add_f32 v[20:21], v[24:25], v[26:27]
	v_pk_add_f32 v[14:15], v[28:29], v[16:17]
	v_pk_add_f32 v[22:23], v[32:33], v[34:35]
	v_pk_add_f32 v[14:15], v[14:15], v[20:21]
	v_pk_add_f32 v[18:19], v[22:23], v[22:23] op_sel:[0,1] op_sel_hi:[1,0]
	v_pk_add_f32 v[14:15], v[14:15], v[14:15] op_sel:[0,1] op_sel_hi:[1,0]
	s_waitcnt vmcnt(4)
	v_add_f32_e32 v36, v38, v39
	v_add_f32_e32 v38, v40, v41
	s_waitcnt vmcnt(3)
	v_mov_b32_e32 v37, v44
	v_mov_b32_e32 v39, v45
	v_mov_b32_e32 v19, v43
	v_mov_b32_e32 v15, v42
	v_pk_add_f32 v[24:25], v[36:37], v[38:39]
	v_pk_add_f32 v[14:15], v[14:15], v[18:19]
	s_nop 0
	v_pk_add_f32 v[14:15], v[14:15], v[24:25]
	s_nop 0
	v_add_f32_e32 v14, v14, v15
	v_fmamk_f32 v14, v14, 0x3a000000, v0
	v_rsq_f32_e32 v26, v14
	s_waitcnt vmcnt(2)
	v_pk_mul_f32 v[14:15], v[26:27], v[46:47] op_sel_hi:[0,1]
	v_pk_mul_f32 v[16:17], v[26:27], v[48:49] op_sel_hi:[0,1]
	s_waitcnt vmcnt(1)
	v_pk_mul_f32 v[16:17], v[16:17], v[52:53]
	v_pk_mul_f32 v[14:15], v[14:15], v[50:51]
	global_store_dwordx4 v[58:59], v[14:17], off offset:-3072 nt
	global_load_dwordx4 v[14:17], v[2:3], off offset:1024
	s_nop 0
	global_load_dwordx4 v[18:21], v[58:59], off offset:-1024
	s_waitcnt vmcnt(3)
	v_pk_mul_f32 v[22:23], v[26:27], v[56:57] op_sel_hi:[0,1]
	v_pk_mul_f32 v[24:25], v[26:27], v[54:55] op_sel_hi:[0,1]
	s_waitcnt vmcnt(1)
	v_pk_mul_f32 v[14:15], v[24:25], v[14:15]
	v_pk_mul_f32 v[16:17], v[22:23], v[16:17]
	global_store_dwordx4 v[58:59], v[14:17], off offset:-2048 nt
	global_load_dwordx4 v[14:17], v[2:3], off offset:2048
	s_nop 0
	global_load_dwordx4 v[22:25], v[12:13], off offset:-4096
	s_waitcnt vmcnt(3)
	v_pk_mul_f32 v[20:21], v[26:27], v[20:21] op_sel_hi:[0,1]
	v_pk_mul_f32 v[18:19], v[26:27], v[18:19] op_sel_hi:[0,1]
	s_waitcnt vmcnt(1)
	v_pk_mul_f32 v[14:15], v[18:19], v[14:15]
	v_pk_mul_f32 v[16:17], v[20:21], v[16:17]
	global_store_dwordx4 v[58:59], v[14:17], off offset:-1024 nt
	global_load_dwordx4 v[14:17], v[2:3], off offset:3072
	s_nop 0
	global_load_dwordx4 v[18:21], v[12:13], off offset:-3072
	s_waitcnt vmcnt(3)
	v_pk_mul_f32 v[24:25], v[26:27], v[24:25] op_sel_hi:[0,1]
	v_pk_mul_f32 v[22:23], v[26:27], v[22:23] op_sel_hi:[0,1]
	s_waitcnt vmcnt(1)
	v_pk_mul_f32 v[14:15], v[22:23], v[14:15]
	v_pk_mul_f32 v[16:17], v[24:25], v[16:17]
	global_store_dwordx4 v[12:13], v[14:17], off offset:-4096 nt
	global_load_dwordx4 v[14:17], v[4:5], off
	s_nop 0
	global_load_dwordx4 v[22:25], v[12:13], off offset:-2048
	s_waitcnt vmcnt(3)
	v_pk_mul_f32 v[20:21], v[26:27], v[20:21] op_sel_hi:[0,1]
	v_pk_mul_f32 v[18:19], v[26:27], v[18:19] op_sel_hi:[0,1]
	s_waitcnt vmcnt(1)
	v_pk_mul_f32 v[14:15], v[18:19], v[14:15]
	v_pk_mul_f32 v[16:17], v[20:21], v[16:17]
	global_store_dwordx4 v[12:13], v[14:17], off offset:-3072 nt
	global_load_dwordx4 v[14:17], v[6:7], off
	s_nop 0
	global_load_dwordx4 v[18:21], v[12:13], off offset:-1024
	s_waitcnt vmcnt(3)
	v_pk_mul_f32 v[24:25], v[26:27], v[24:25] op_sel_hi:[0,1]
	v_pk_mul_f32 v[22:23], v[26:27], v[22:23] op_sel_hi:[0,1]
	s_waitcnt vmcnt(1)
	v_pk_mul_f32 v[14:15], v[22:23], v[14:15]
	v_pk_mul_f32 v[16:17], v[24:25], v[16:17]
	global_store_dwordx4 v[12:13], v[14:17], off offset:-2048 nt
	global_load_dwordx4 v[14:17], v[8:9], off
	s_nop 0
	global_load_dwordx4 v[22:25], v[12:13], off
	s_waitcnt vmcnt(3)
	v_pk_mul_f32 v[20:21], v[26:27], v[20:21] op_sel_hi:[0,1]
	v_pk_mul_f32 v[18:19], v[26:27], v[18:19] op_sel_hi:[0,1]
	s_waitcnt vmcnt(1)
	v_pk_mul_f32 v[14:15], v[18:19], v[14:15]
	v_pk_mul_f32 v[16:17], v[20:21], v[16:17]
	global_store_dwordx4 v[12:13], v[14:17], off offset:-1024 nt
	global_load_dwordx4 v[14:17], v[10:11], off
	s_waitcnt vmcnt(2)
	v_pk_mul_f32 v[18:19], v[26:27], v[24:25] op_sel_hi:[0,1]
	v_pk_mul_f32 v[20:21], v[26:27], v[22:23] op_sel_hi:[0,1]
	s_waitcnt vmcnt(0)
	v_pk_mul_f32 v[14:15], v[20:21], v[14:15]
	v_pk_mul_f32 v[16:17], v[18:19], v[16:17]
	global_store_dwordx4 v[12:13], v[14:17], off nt
	v_lshl_add_u64 v[12:13], v[12:13], 0, s[6:7]
	s_cbranch_scc1 .LBB0_1185
